# y batch alignment: partials 0..5 finish the carried batch, 6..21 form the in-trip batch
# speedup vs baseline: 1.0375x; 1.0005x over previous
; __device__ __forceinline__ void phase_scan(const Params& p, LAS unsigned char* lds) {
;     ...
;         f32x2 S01 = {0.f, 0.f}, S23 = {0.f, 0.f};
.Lscan_init:
	v_mov_b64_e32 v[2:3], 0
	v_mov_b64_e32 v[4:5], 0
	v_mov_b64_e32 v[6:7], 0
	v_mov_b64_e32 v[8:9], 0
	v_mov_b64_e32 v[10:11], 0
	v_mov_b64_e32 v[12:13], 0
	v_mov_b64_e32 v[14:15], 0
	v_mov_b64_e32 v[16:17], 0
	v_mov_b64_e32 v[18:19], 0
	v_mov_b64_e32 v[20:21], 0
	v_mov_b64_e32 v[22:23], 0
	v_mov_b64_e32 v[24:25], 0
	v_mov_b64_e32 v[26:27], 0
	v_mov_b64_e32 v[28:29], 0
	v_mov_b64_e32 v[30:31], 0
	v_mov_b64_e32 v[32:33], 0
	v_mov_b64_e32 v[34:35], 0
	v_mov_b64_e32 v[36:37], 0
	v_mov_b64_e32 v[38:39], 0
	v_mov_b64_e32 v[40:41], 0
	v_mov_b64_e32 v[42:43], 0
	v_mov_b64_e32 v[44:45], 0
	v_mov_b64_e32 v[46:47], 0
	v_mov_b64_e32 v[48:49], 0
	v_mov_b64_e32 v[50:51], 0
	v_mov_b64_e32 v[52:53], 0
	v_mov_b64_e32 v[54:55], 0
	v_mov_b64_e32 v[56:57], 0
	v_mov_b64_e32 v[58:59], 0
	v_mov_b64_e32 v[60:61], 0
	v_mov_b64_e32 v[62:63], 0
	v_mov_b64_e32 v[64:65], 0
	v_mov_b64_e32 v[66:67], 0
	v_mov_b64_e32 v[68:69], 0
	v_mov_b64_e32 v[70:71], 0
	v_mov_b64_e32 v[72:73], 0
	v_mov_b64_e32 v[74:75], 0
	v_mov_b64_e32 v[76:77], 0
	v_mov_b64_e32 v[78:79], 0
	v_mov_b64_e32 v[80:81], 0
	v_mov_b64_e32 v[110:111], 0
	v_mov_b64_e32 v[112:113], 0
	v_mov_b64_e32 v[204:205], 0
	v_mov_b64_e32 v[206:207], 0
	v_mov_b64_e32 v[208:209], 0
	v_mov_b64_e32 v[210:211], 0
	v_mov_b64_e32 v[212:213], 0
	s_mov_b32 s34, 0x22222222
	s_mov_b32 s35, 0x22222222
	s_mov_b32 s56, 0x44444444
	s_mov_b32 s57, 0x44444444
	s_mov_b32 s98, 0x88888888
	s_mov_b32 s99, 0x88888888
	s_cmp_lg_u64 s[8:9], 0
	s_mov_b32 s100, 0xffff0000
	s_cselect_b32 s100, 0x10000, s100
	s_cselect_b32 s101, 0, -1
	v_and_b32_e32 v202, 15, v130
	v_add_u32_e32 v202, 2, v202
	v_sub_u32_e32 v203, 0x1fff, v202
	v_cndmask_b32_e64 v202, v203, v202, s[8:9]
	v_add_u32_e32 v202, s79, v202
	v_mov_b32_e32 v203, 0
	v_lshlrev_b64 v[126:127], 11, v[202:203]
	v_lshl_add_u64 v[126:127], s[48:49], 0, v[126:127]
	s_lshl_b32 s14, s80, 1
	s_add_u32 s14, s14, s20
	s_mov_b32 s15, 0
	v_lshl_add_u64 v[126:127], v[126:127], 0, s[14:15]
	v_lshrrev_b32_e32 v202, 6, v179
	v_lshl_add_u64 v[126:127], v[126:127], 0, v[202:203]
	s_ashr_i64 s[14:15], s[100:101], 1
	s_sub_u32 s14, 0, s14
	s_subb_u32 s15, 0, s15
	v_lshl_add_u64 v[128:129], v[126:127], 0, s[14:15]
	s_branch .LBB0_604

; __device__ __forceinline__ void phase_scan(const Params& p, LAS unsigned char* lds) {
;     ...
;             if (wave < 4) {
;                 if (n >= 0) {
;                     __builtin_amdgcn_s_setprio(3);
;                     const LAS float* sR = OPS + (n & 1) * SET_F + j0; const LAS float* sW = sR + 2048; const LAS float* sK = sW + 2048; const LAS float* sA = sK + 2048; const LAS float* sB = sA + 2048; const LAS float* sV = OPS + (n & 1) * SET_F + 10240;
;                     LAS float* sY = sYb + (n & 1) * 512;
;                     f32x4 a_ = *(const LAS f32x4*)(sA), w_ = *(const LAS f32x4*)(sW), b_ = *(const LAS f32x4*)(sB);
;                     f32x4 k_ = *(const LAS f32x4*)(sK), r_ = *(const LAS f32x4*)(sR);
;                     f32x4 vq[4];
; #pragma unroll
;                     for (int u = 0; u < 4; ++u) vq[u] = *(const LAS f32x4*)(sV + srow * 32 + 4 * u);
;                     f32x4 rp = r_;
; #pragma unroll
;                     for (int hb = 0; hb < 2; ++hb) {
;                         f32x4 vn[4];
; #pragma unroll
;                         for (int u = 0; u < 4; ++u) vn[u] = *(const LAS f32x4*)(sV + srow * 32 + ((16 * (hb + 1)) & 31) + 4 * u);
; #pragma unroll
;                         for (int u16 = 0; u16 < 16; ++u16) {
;                             const int s = 16 * hb + u16;
;                             const int sn = (s + 1) & 31;
;                             const f32x4 a_n = *(const LAS f32x4*)(sA + sn * 64), w_n = *(const LAS f32x4*)(sW + sn * 64), b_n = *(const LAS f32x4*)(sB + sn * 64);
;                             const f32x4 k_n = *(const LAS f32x4*)(sK + sn * 64), r_n = *(const LAS f32x4*)(sR + sn * 64);
;                             const float v = vq[u16 >> 2][u16 & 3];
;                             const f32x2 vv = {v, v};
;                             f32x2 pp = S01 * (f32x2){a_[0], a_[1]}; pp = S23 * (f32x2){a_[2], a_[3]} + pp;
;                             f32x2 yy = S01 * (f32x2){rp[0], rp[1]}; yy = S23 * (f32x2){rp[2], rp[3]} + yy;
;                             float sa = pp[0] + pp[1], y = yy[0] + yy[1];
;                             sa += dpp_f<0xB1>(sa); y += dpp_f<0xB1>(y);
;                             sa += dpp_f<0x4E>(sa); y += dpp_f<0x4E>(y);
;                             sa += dpp_f<0x141>(sa); y += dpp_f<0x141>(y);
;                             sa += dpp_f<0x140>(sa); y += dpp_f<0x140>(y);
.Lscan_wave_top:
	s_mov_b64 s[54:55], 0
	s_cmp_lt_i32 s81, 0
	s_cbranch_scc1 .LBB0_603
	s_setprio 3
	s_and_b32 s14, s81, 1
	s_mul_i32 s15, s14, 0xa800
	s_add_i32 s15, s15, 0x8800
	v_add_u32_e32 v124, s15, v178
	v_add_u32_e32 v125, s15, v179
	s_cmp_eq_u32 s81, 0
	s_cselect_b32 s14, 0xc000c000, -1
	s_mov_b32 s15, s14
	v_pk_mul_f32 v[114:115], v[166:167], v[22:23]
	v_pk_mul_f32 v[116:117], v[166:167], v[18:19]
	v_pk_fma_f32 v[114:115], v[164:165], v[24:25], v[114:115]
	v_pk_fma_f32 v[116:117], v[164:165], v[20:21], v[116:117]
	v_add_f32_e32 v122, v114, v115
	v_pk_mul_f32 v[118:119], v[110:111], v[34:35] op_sel:[1,0]
	v_add_f32_e32 v214, v116, v117
	v_add_f32_dpp v122, v122, v122 quad_perm:[1,0,3,2] row_mask:0xf bank_mask:0xf bound_ctrl:1
	v_pk_mul_f32 v[120:121], v[110:111], v[36:37] op_sel:[1,0]
	ds_read_b128 v[14:17], v124 offset:16384
	v_add_f32_dpp v122, v122, v122 quad_perm:[2,3,0,1] row_mask:0xf bank_mask:0xf bound_ctrl:1
	v_pk_fma_f32 v[166:167], v[166:167], v[26:27], v[118:119]
	ds_read_b128 v[6:9], v124 offset:8192
	v_add_f32_dpp v122, v122, v122 row_half_mirror row_mask:0xf bank_mask:0xf bound_ctrl:1
	v_pk_fma_f32 v[164:165], v[164:165], v[28:29], v[120:121]
	ds_read_b128 v[10:13], v124 offset:32768
	v_add_f32_dpp v122, v122, v122 row_mirror row_mask:0xf bank_mask:0xf bound_ctrl:1
	v_add_f32_dpp v204, v204, v204 row_mirror row_mask:0xf bank_mask:0xf bound_ctrl:1
	v_add_f32_dpp v204, v212, v212 row_mirror row_mask:0xf bank_mask:0xc bound_ctrl:1
	v_pk_fma_f32 v[166:167], v[30:31], v[122:123], v[166:167] op_sel_hi:[1,0,1]
	v_pk_fma_f32 v[164:165], v[32:33], v[122:123], v[164:165] op_sel_hi:[1,0,1]
	ds_read_b128 v[18:21], v124 offset:0
	ds_read_b128 v[2:5], v124 offset:24576
	ds_read_b128 v[82:85], v125 offset:40960
	v_pk_mul_f32 v[114:115], v[166:167], v[42:43]
	v_pk_mul_f32 v[116:117], v[166:167], v[38:39]
	v_pk_fma_f32 v[114:115], v[164:165], v[44:45], v[114:115]
	v_pk_fma_f32 v[116:117], v[164:165], v[40:41], v[116:117]
	v_add_f32_e32 v122, v114, v115
	v_pk_mul_f32 v[118:119], v[112:113], v[54:55] op_sel_hi:[0,1]
	v_add_f32_e32 v215, v116, v117
	v_add_f32_dpp v122, v122, v122 quad_perm:[1,0,3,2] row_mask:0xf bank_mask:0xf bound_ctrl:1
	v_pk_mul_f32 v[120:121], v[112:113], v[56:57] op_sel_hi:[0,1]
	ds_read_b128 v[34:37], v124 offset:16640
	v_add_f32_dpp v122, v122, v122 quad_perm:[2,3,0,1] row_mask:0xf bank_mask:0xf bound_ctrl:1
	v_pk_fma_f32 v[166:167], v[166:167], v[46:47], v[118:119]
	ds_read_b128 v[26:29], v124 offset:8448
	v_add_f32_dpp v122, v122, v122 row_half_mirror row_mask:0xf bank_mask:0xf bound_ctrl:1
	v_pk_fma_f32 v[164:165], v[164:165], v[48:49], v[120:121]
	ds_read_b128 v[30:33], v124 offset:33024
	v_add_f32_dpp v122, v122, v122 row_mirror row_mask:0xf bank_mask:0xf bound_ctrl:1
	v_add_f32_dpp v205, v205, v205 row_mirror row_mask:0xf bank_mask:0xf bound_ctrl:1
	v_add_f32_dpp v205, v213, v213 row_mirror row_mask:0xf bank_mask:0xc bound_ctrl:1
	v_pk_fma_f32 v[166:167], v[50:51], v[122:123], v[166:167] op_sel_hi:[1,0,1]
	v_pk_fma_f32 v[164:165], v[52:53], v[122:123], v[164:165] op_sel_hi:[1,0,1]
	ds_read_b128 v[38:41], v124 offset:256
	ds_read_b128 v[22:25], v124 offset:24832
	v_pk_mul_f32 v[114:115], v[166:167], v[62:63]
	v_pk_mul_f32 v[116:117], v[166:167], v[58:59]
	v_pk_fma_f32 v[114:115], v[164:165], v[64:65], v[114:115]
	v_pk_fma_f32 v[116:117], v[164:165], v[60:61], v[116:117]
	v_add_f32_e32 v122, v114, v115
	v_pk_mul_f32 v[118:119], v[112:113], v[74:75] op_sel:[1,0]
	v_add_f32_e32 v216, v116, v117
	v_add_f32_dpp v122, v122, v122 quad_perm:[1,0,3,2] row_mask:0xf bank_mask:0xf bound_ctrl:1
	v_pk_mul_f32 v[120:121], v[112:113], v[76:77] op_sel:[1,0]
	ds_read_b128 v[54:57], v124 offset:16896
	v_add_f32_dpp v122, v122, v122 quad_perm:[2,3,0,1] row_mask:0xf bank_mask:0xf bound_ctrl:1
	v_pk_fma_f32 v[166:167], v[166:167], v[66:67], v[118:119]
	ds_read_b128 v[46:49], v124 offset:8704
	v_add_f32_dpp v122, v122, v122 row_half_mirror row_mask:0xf bank_mask:0xf bound_ctrl:1
	v_pk_fma_f32 v[164:165], v[164:165], v[68:69], v[120:121]
	ds_read_b128 v[50:53], v124 offset:33280
	v_add_f32_dpp v122, v122, v122 row_mirror row_mask:0xf bank_mask:0xf bound_ctrl:1
	v_add_f32_dpp v206, v206, v206 row_mirror row_mask:0xf bank_mask:0xf bound_ctrl:1
	v_add_f32_dpp v206, v214, v214 row_mirror row_mask:0xf bank_mask:0xc bound_ctrl:1
	v_pk_fma_f32 v[166:167], v[70:71], v[122:123], v[166:167] op_sel_hi:[1,0,1]
	v_pk_fma_f32 v[164:165], v[72:73], v[122:123], v[164:165] op_sel_hi:[1,0,1]
	ds_read_b128 v[58:61], v124 offset:512
	ds_read_b128 v[42:45], v124 offset:25088
	s_waitcnt lgkmcnt(11)
	v_pk_mul_f32 v[114:115], v[166:167], v[2:3]
	v_pk_mul_f32 v[116:117], v[166:167], v[78:79]
	v_pk_fma_f32 v[114:115], v[164:165], v[4:5], v[114:115]
	v_pk_fma_f32 v[116:117], v[164:165], v[80:81], v[116:117]
	v_add_f32_e32 v122, v114, v115
	s_waitcnt lgkmcnt(10)
	v_pk_mul_f32 v[118:119], v[82:83], v[14:15] op_sel_hi:[0,1]
	v_add_f32_e32 v217, v116, v117
	v_add_f32_dpp v122, v122, v122 quad_perm:[1,0,3,2] row_mask:0xf bank_mask:0xf bound_ctrl:1
	v_pk_mul_f32 v[120:121], v[82:83], v[16:17] op_sel_hi:[0,1]
	ds_read_b128 v[74:77], v124 offset:17152
	v_add_f32_dpp v122, v122, v122 quad_perm:[2,3,0,1] row_mask:0xf bank_mask:0xf bound_ctrl:1
	v_pk_fma_f32 v[166:167], v[166:167], v[6:7], v[118:119]
	ds_read_b128 v[66:69], v124 offset:8960
	v_add_f32_dpp v122, v122, v122 row_half_mirror row_mask:0xf bank_mask:0xf bound_ctrl:1
	v_pk_fma_f32 v[164:165], v[164:165], v[8:9], v[120:121]
	ds_read_b128 v[70:73], v124 offset:33536
	v_add_f32_dpp v122, v122, v122 row_mirror row_mask:0xf bank_mask:0xf bound_ctrl:1
	v_add_f32_dpp v207, v207, v207 row_mirror row_mask:0xf bank_mask:0xf bound_ctrl:1
	v_add_f32_dpp v207, v215, v215 row_mirror row_mask:0xf bank_mask:0xc bound_ctrl:1
	v_pk_fma_f32 v[166:167], v[10:11], v[122:123], v[166:167] op_sel_hi:[1,0,1]
	v_pk_fma_f32 v[164:165], v[12:13], v[122:123], v[164:165] op_sel_hi:[1,0,1]
	ds_read_b128 v[78:81], v124 offset:768
	ds_read_b128 v[62:65], v124 offset:25344
	s_waitcnt lgkmcnt(10)
; #define LAS __attribute__((address_space(3)))
; template <int CTRL> __device__ __forceinline__ float dpp_f(float x) { return __int_as_float(__builtin_amdgcn_update_dpp(0, __float_as_int(x), CTRL, 0xf, 0xf, false)); }
; __device__ __forceinline__ void phase_scan(const Params& p, LAS unsigned char* lds) {
;     ...
;                         for (int u16 = 0; u16 < 16; ++u16) {
;                             const int s = 16 * hb + u16;
;                             const int sn = (s + 1) & 31;
;                             const f32x4 a_n = *(const LAS f32x4*)(sA + sn * 64), w_n = *(const LAS f32x4*)(sW + sn * 64), b_n = *(const LAS f32x4*)(sB + sn * 64);
;                             const f32x4 k_n = *(const LAS f32x4*)(sK + sn * 64), r_n = *(const LAS f32x4*)(sR + sn * 64);
;                             const float v = vq[u16 >> 2][u16 & 3];
;                             const f32x2 vv = {v, v};
;                             f32x2 pp = S01 * (f32x2){a_[0], a_[1]}; pp = S23 * (f32x2){a_[2], a_[3]} + pp;
;                             f32x2 yy = S01 * (f32x2){rp[0], rp[1]}; yy = S23 * (f32x2){rp[2], rp[3]} + yy;
;                             float sa = pp[0] + pp[1], y = yy[0] + yy[1];
;                             sa += dpp_f<0xB1>(sa); y += dpp_f<0xB1>(y);
;                             sa += dpp_f<0x4E>(sa); y += dpp_f<0x4E>(y);
;                             sa += dpp_f<0x141>(sa); y += dpp_f<0x141>(y);
;                             sa += dpp_f<0x140>(sa); y += dpp_f<0x140>(y);
;                             sY[((s - 1) & 31) * 16 + srow] = y;
;                             const f32x2 sv = {sa, sa};
;                             S01 = S01 * (f32x2){w_[0], w_[1]} + vv * (f32x2){k_[0], k_[1]};
;                             S23 = S23 * (f32x2){w_[2], w_[3]} + vv * (f32x2){k_[2], k_[3]};
;                             S01 = sv * (f32x2){b_[0], b_[1]} + S01;
;                             S23 = sv * (f32x2){b_[2], b_[3]} + S23;
;                             rp = r_;
;                             a_ = a_n; w_ = w_n; b_ = b_n; k_ = k_n; r_ = r_n;
;                         }
	v_pk_mul_f32 v[114:115], v[166:167], v[22:23]
	v_pk_mul_f32 v[116:117], v[166:167], v[18:19]
	v_pk_fma_f32 v[114:115], v[164:165], v[24:25], v[114:115]
	v_pk_fma_f32 v[116:117], v[164:165], v[20:21], v[116:117]
	v_add_f32_e32 v122, v114, v115
	v_pk_mul_f32 v[118:119], v[82:83], v[34:35] op_sel:[1,0]
	v_add_f32_e32 v218, v116, v117
	v_add_f32_dpp v122, v122, v122 quad_perm:[1,0,3,2] row_mask:0xf bank_mask:0xf bound_ctrl:1
	v_pk_mul_f32 v[120:121], v[82:83], v[36:37] op_sel:[1,0]
	ds_read_b128 v[14:17], v124 offset:17408
	v_add_f32_dpp v122, v122, v122 quad_perm:[2,3,0,1] row_mask:0xf bank_mask:0xf bound_ctrl:1
	v_pk_fma_f32 v[166:167], v[166:167], v[26:27], v[118:119]
	ds_read_b128 v[6:9], v124 offset:9216
	v_add_f32_dpp v122, v122, v122 row_half_mirror row_mask:0xf bank_mask:0xf bound_ctrl:1
	v_pk_fma_f32 v[164:165], v[164:165], v[28:29], v[120:121]
	ds_read_b128 v[10:13], v124 offset:33792
	v_add_f32_dpp v122, v122, v122 row_mirror row_mask:0xf bank_mask:0xf bound_ctrl:1
	v_add_f32_dpp v208, v208, v208 row_mirror row_mask:0xf bank_mask:0xf bound_ctrl:1
	v_add_f32_dpp v208, v216, v216 row_mirror row_mask:0xf bank_mask:0xc bound_ctrl:1
	v_pk_fma_f32 v[166:167], v[30:31], v[122:123], v[166:167] op_sel_hi:[1,0,1]
	v_pk_fma_f32 v[164:165], v[32:33], v[122:123], v[164:165] op_sel_hi:[1,0,1]
	ds_read_b128 v[18:21], v124 offset:1024
	ds_read_b128 v[2:5], v124 offset:25600
	ds_read_b128 v[86:89], v125 offset:40976
	s_waitcnt lgkmcnt(11)
	v_pk_mul_f32 v[114:115], v[166:167], v[42:43]
	v_pk_mul_f32 v[116:117], v[166:167], v[38:39]
	v_pk_fma_f32 v[114:115], v[164:165], v[44:45], v[114:115]
	v_pk_fma_f32 v[116:117], v[164:165], v[40:41], v[116:117]
	v_add_f32_e32 v122, v114, v115
	v_pk_mul_f32 v[118:119], v[84:85], v[54:55] op_sel_hi:[0,1]
	v_add_f32_e32 v219, v116, v117
	v_add_f32_dpp v122, v122, v122 quad_perm:[1,0,3,2] row_mask:0xf bank_mask:0xf bound_ctrl:1
	v_pk_mul_f32 v[120:121], v[84:85], v[56:57] op_sel_hi:[0,1]
	ds_read_b128 v[34:37], v124 offset:17664
	v_add_f32_dpp v122, v122, v122 quad_perm:[2,3,0,1] row_mask:0xf bank_mask:0xf bound_ctrl:1
	v_pk_fma_f32 v[166:167], v[166:167], v[46:47], v[118:119]
	ds_read_b128 v[26:29], v124 offset:9472
	v_add_f32_dpp v122, v122, v122 row_half_mirror row_mask:0xf bank_mask:0xf bound_ctrl:1
	v_pk_fma_f32 v[164:165], v[164:165], v[48:49], v[120:121]
	ds_read_b128 v[30:33], v124 offset:34048
	v_add_f32_dpp v122, v122, v122 row_mirror row_mask:0xf bank_mask:0xf bound_ctrl:1
	v_add_f32_dpp v209, v209, v209 row_mirror row_mask:0xf bank_mask:0xf bound_ctrl:1
	v_add_f32_dpp v209, v217, v217 row_mirror row_mask:0xf bank_mask:0xc bound_ctrl:1
	v_pk_fma_f32 v[166:167], v[50:51], v[122:123], v[166:167] op_sel_hi:[1,0,1]
	v_pk_fma_f32 v[164:165], v[52:53], v[122:123], v[164:165] op_sel_hi:[1,0,1]
	ds_read_b128 v[38:41], v124 offset:1280
	ds_read_b128 v[22:25], v124 offset:25856
	s_waitcnt lgkmcnt(11)
	v_pk_mul_f32 v[114:115], v[166:167], v[62:63]
	v_pk_mul_f32 v[116:117], v[166:167], v[58:59]
	v_pk_fma_f32 v[114:115], v[164:165], v[64:65], v[114:115]
	v_pk_fma_f32 v[116:117], v[164:165], v[60:61], v[116:117]
	v_add_f32_e32 v122, v114, v115
	v_pk_mul_f32 v[118:119], v[84:85], v[74:75] op_sel:[1,0]
	v_add_f32_e32 v220, v116, v117
	v_add_f32_dpp v122, v122, v122 quad_perm:[1,0,3,2] row_mask:0xf bank_mask:0xf bound_ctrl:1
	v_pk_mul_f32 v[120:121], v[84:85], v[76:77] op_sel:[1,0]
	ds_read_b128 v[54:57], v124 offset:17920
	v_add_f32_dpp v122, v122, v122 quad_perm:[2,3,0,1] row_mask:0xf bank_mask:0xf bound_ctrl:1
	v_pk_fma_f32 v[166:167], v[166:167], v[66:67], v[118:119]
	ds_read_b128 v[46:49], v124 offset:9728
	v_add_f32_dpp v122, v122, v122 row_half_mirror row_mask:0xf bank_mask:0xf bound_ctrl:1
	v_pk_fma_f32 v[164:165], v[164:165], v[68:69], v[120:121]
	ds_read_b128 v[50:53], v124 offset:34304
	v_add_f32_dpp v122, v122, v122 row_mirror row_mask:0xf bank_mask:0xf bound_ctrl:1
	v_add_f32_dpp v210, v210, v210 row_mirror row_mask:0xf bank_mask:0xf bound_ctrl:1
	v_add_f32_dpp v210, v218, v218 row_mirror row_mask:0xf bank_mask:0xc bound_ctrl:1
	v_pk_fma_f32 v[166:167], v[70:71], v[122:123], v[166:167] op_sel_hi:[1,0,1]
	v_pk_fma_f32 v[164:165], v[72:73], v[122:123], v[164:165] op_sel_hi:[1,0,1]
	ds_read_b128 v[58:61], v124 offset:1536
	ds_read_b128 v[42:45], v124 offset:26112
	s_waitcnt lgkmcnt(11)
	v_pk_mul_f32 v[114:115], v[166:167], v[2:3]
	v_pk_mul_f32 v[116:117], v[166:167], v[78:79]
	v_pk_fma_f32 v[114:115], v[164:165], v[4:5], v[114:115]
	v_pk_fma_f32 v[116:117], v[164:165], v[80:81], v[116:117]
	v_add_f32_e32 v122, v114, v115
	s_waitcnt lgkmcnt(10)
	v_pk_mul_f32 v[118:119], v[86:87], v[14:15] op_sel_hi:[0,1]
	v_add_f32_e32 v221, v116, v117
	v_add_f32_dpp v122, v122, v122 quad_perm:[1,0,3,2] row_mask:0xf bank_mask:0xf bound_ctrl:1
	v_pk_mul_f32 v[120:121], v[86:87], v[16:17] op_sel_hi:[0,1]
	ds_read_b128 v[74:77], v124 offset:18176
	v_add_f32_dpp v122, v122, v122 quad_perm:[2,3,0,1] row_mask:0xf bank_mask:0xf bound_ctrl:1
	v_pk_fma_f32 v[166:167], v[166:167], v[6:7], v[118:119]
	ds_read_b128 v[66:69], v124 offset:9984
	v_add_f32_dpp v122, v122, v122 row_half_mirror row_mask:0xf bank_mask:0xf bound_ctrl:1
	v_pk_fma_f32 v[164:165], v[164:165], v[8:9], v[120:121]
	ds_read_b128 v[70:73], v124 offset:34560
	v_add_f32_dpp v122, v122, v122 row_mirror row_mask:0xf bank_mask:0xf bound_ctrl:1
	v_add_f32_dpp v211, v211, v211 row_mirror row_mask:0xf bank_mask:0xf bound_ctrl:1
	v_add_f32_dpp v211, v219, v219 row_mirror row_mask:0xf bank_mask:0xc bound_ctrl:1
	v_pk_fma_f32 v[166:167], v[10:11], v[122:123], v[166:167] op_sel_hi:[1,0,1]
	v_pk_fma_f32 v[164:165], v[12:13], v[122:123], v[164:165] op_sel_hi:[1,0,1]
	ds_read_b128 v[78:81], v124 offset:1792
	ds_read_b128 v[62:65], v124 offset:26368
	s_waitcnt lgkmcnt(10)
; #define LAS __attribute__((address_space(3)))
; template <int CTRL> __device__ __forceinline__ float dpp_f(float x) { return __int_as_float(__builtin_amdgcn_update_dpp(0, __float_as_int(x), CTRL, 0xf, 0xf, false)); }
; __device__ __forceinline__ void phase_scan(const Params& p, LAS unsigned char* lds) {
;     ...
;                         for (int u16 = 0; u16 < 16; ++u16) {
;                             const int s = 16 * hb + u16;
;                             const int sn = (s + 1) & 31;
;                             const f32x4 a_n = *(const LAS f32x4*)(sA + sn * 64), w_n = *(const LAS f32x4*)(sW + sn * 64), b_n = *(const LAS f32x4*)(sB + sn * 64);
;                             const f32x4 k_n = *(const LAS f32x4*)(sK + sn * 64), r_n = *(const LAS f32x4*)(sR + sn * 64);
;                             const float v = vq[u16 >> 2][u16 & 3];
;                             const f32x2 vv = {v, v};
;                             f32x2 pp = S01 * (f32x2){a_[0], a_[1]}; pp = S23 * (f32x2){a_[2], a_[3]} + pp;
;                             f32x2 yy = S01 * (f32x2){rp[0], rp[1]}; yy = S23 * (f32x2){rp[2], rp[3]} + yy;
;                             float sa = pp[0] + pp[1], y = yy[0] + yy[1];
;                             sa += dpp_f<0xB1>(sa); y += dpp_f<0xB1>(y);
;                             sa += dpp_f<0x4E>(sa); y += dpp_f<0x4E>(y);
;                             sa += dpp_f<0x141>(sa); y += dpp_f<0x141>(y);
;                             sa += dpp_f<0x140>(sa); y += dpp_f<0x140>(y);
;                             sY[((s - 1) & 31) * 16 + srow] = y;
;                             const f32x2 sv = {sa, sa};
;                             S01 = S01 * (f32x2){w_[0], w_[1]} + vv * (f32x2){k_[0], k_[1]};
;                             S23 = S23 * (f32x2){w_[2], w_[3]} + vv * (f32x2){k_[2], k_[3]};
;                             S01 = sv * (f32x2){b_[0], b_[1]} + S01;
;                             S23 = sv * (f32x2){b_[2], b_[3]} + S23;
;                             rp = r_;
;                             a_ = a_n; w_ = w_n; b_ = b_n; k_ = k_n; r_ = r_n;
;                         }
	v_pk_mul_f32 v[114:115], v[166:167], v[22:23]
	v_pk_mul_f32 v[116:117], v[166:167], v[18:19]
	v_pk_fma_f32 v[114:115], v[164:165], v[24:25], v[114:115]
	v_pk_fma_f32 v[116:117], v[164:165], v[20:21], v[116:117]
	v_add_f32_e32 v122, v114, v115
	v_pk_mul_f32 v[118:119], v[86:87], v[34:35] op_sel:[1,0]
	v_add_f32_e32 v222, v116, v117
	v_add_f32_dpp v122, v122, v122 quad_perm:[1,0,3,2] row_mask:0xf bank_mask:0xf bound_ctrl:1
	v_pk_mul_f32 v[120:121], v[86:87], v[36:37] op_sel:[1,0]
	ds_read_b128 v[14:17], v124 offset:18432
	v_add_f32_dpp v122, v122, v122 quad_perm:[2,3,0,1] row_mask:0xf bank_mask:0xf bound_ctrl:1
	v_pk_fma_f32 v[166:167], v[166:167], v[26:27], v[118:119]
	ds_read_b128 v[6:9], v124 offset:10240
	v_add_f32_dpp v122, v122, v122 row_half_mirror row_mask:0xf bank_mask:0xf bound_ctrl:1
	v_pk_fma_f32 v[164:165], v[164:165], v[28:29], v[120:121]
	ds_read_b128 v[10:13], v124 offset:34816
	v_add_f32_dpp v122, v122, v122 row_mirror row_mask:0xf bank_mask:0xf bound_ctrl:1
	v_add_f32_dpp v204, v204, v204 row_half_mirror row_mask:0xf bank_mask:0xf bound_ctrl:1
	v_add_f32_dpp v205, v205, v205 row_half_mirror row_mask:0xf bank_mask:0xf bound_ctrl:1
	v_pk_fma_f32 v[166:167], v[30:31], v[122:123], v[166:167] op_sel_hi:[1,0,1]
	v_pk_fma_f32 v[164:165], v[32:33], v[122:123], v[164:165] op_sel_hi:[1,0,1]
	ds_read_b128 v[18:21], v124 offset:2048
	ds_read_b128 v[2:5], v124 offset:26624
	ds_read_b128 v[90:93], v125 offset:40992
	s_waitcnt lgkmcnt(11)
	v_pk_mul_f32 v[114:115], v[166:167], v[42:43]
	v_pk_mul_f32 v[116:117], v[166:167], v[38:39]
	v_pk_fma_f32 v[114:115], v[164:165], v[44:45], v[114:115]
	v_pk_fma_f32 v[116:117], v[164:165], v[40:41], v[116:117]
	v_add_f32_e32 v122, v114, v115
	v_pk_mul_f32 v[118:119], v[88:89], v[54:55] op_sel_hi:[0,1]
	v_add_f32_e32 v223, v116, v117
	v_add_f32_dpp v122, v122, v122 quad_perm:[1,0,3,2] row_mask:0xf bank_mask:0xf bound_ctrl:1
	v_pk_mul_f32 v[120:121], v[88:89], v[56:57] op_sel_hi:[0,1]
	ds_read_b128 v[34:37], v124 offset:18688
	v_add_f32_dpp v122, v122, v122 quad_perm:[2,3,0,1] row_mask:0xf bank_mask:0xf bound_ctrl:1
	v_pk_fma_f32 v[166:167], v[166:167], v[46:47], v[118:119]
	ds_read_b128 v[26:29], v124 offset:10496
	v_add_f32_dpp v122, v122, v122 row_half_mirror row_mask:0xf bank_mask:0xf bound_ctrl:1
	v_pk_fma_f32 v[164:165], v[164:165], v[48:49], v[120:121]
	ds_read_b128 v[30:33], v124 offset:35072
	v_add_f32_dpp v122, v122, v122 row_mirror row_mask:0xf bank_mask:0xf bound_ctrl:1
	v_add_f32_dpp v206, v206, v206 row_half_mirror row_mask:0xf bank_mask:0xf bound_ctrl:1
	v_add_f32_dpp v207, v207, v207 row_half_mirror row_mask:0xf bank_mask:0xf bound_ctrl:1
	v_pk_fma_f32 v[166:167], v[50:51], v[122:123], v[166:167] op_sel_hi:[1,0,1]
	v_pk_fma_f32 v[164:165], v[52:53], v[122:123], v[164:165] op_sel_hi:[1,0,1]
	ds_read_b128 v[38:41], v124 offset:2304
	ds_read_b128 v[22:25], v124 offset:26880
	s_waitcnt lgkmcnt(11)
	v_pk_mul_f32 v[114:115], v[166:167], v[62:63]
	v_pk_mul_f32 v[116:117], v[166:167], v[58:59]
	v_pk_fma_f32 v[114:115], v[164:165], v[64:65], v[114:115]
	v_pk_fma_f32 v[116:117], v[164:165], v[60:61], v[116:117]
	v_add_f32_e32 v122, v114, v115
	v_pk_mul_f32 v[118:119], v[88:89], v[74:75] op_sel:[1,0]
	v_add_f32_e32 v224, v116, v117
	v_add_f32_dpp v122, v122, v122 quad_perm:[1,0,3,2] row_mask:0xf bank_mask:0xf bound_ctrl:1
	v_pk_mul_f32 v[120:121], v[88:89], v[76:77] op_sel:[1,0]
	ds_read_b128 v[54:57], v124 offset:18944
	v_add_f32_dpp v122, v122, v122 quad_perm:[2,3,0,1] row_mask:0xf bank_mask:0xf bound_ctrl:1
	v_pk_fma_f32 v[166:167], v[166:167], v[66:67], v[118:119]
	ds_read_b128 v[46:49], v124 offset:10752
	v_add_f32_dpp v122, v122, v122 row_half_mirror row_mask:0xf bank_mask:0xf bound_ctrl:1
	v_pk_fma_f32 v[164:165], v[164:165], v[68:69], v[120:121]
	ds_read_b128 v[50:53], v124 offset:35328
	v_add_f32_dpp v122, v122, v122 row_mirror row_mask:0xf bank_mask:0xf bound_ctrl:1
	v_add_f32_dpp v204, v208, v208 row_half_mirror row_mask:0xf bank_mask:0xa bound_ctrl:1
	v_add_f32_dpp v205, v209, v209 row_half_mirror row_mask:0xf bank_mask:0xa bound_ctrl:1
	v_pk_fma_f32 v[166:167], v[70:71], v[122:123], v[166:167] op_sel_hi:[1,0,1]
	v_pk_fma_f32 v[164:165], v[72:73], v[122:123], v[164:165] op_sel_hi:[1,0,1]
	ds_read_b128 v[58:61], v124 offset:2560
	ds_read_b128 v[42:45], v124 offset:27136
	s_waitcnt lgkmcnt(11)
	v_pk_mul_f32 v[114:115], v[166:167], v[2:3]
	v_pk_mul_f32 v[116:117], v[166:167], v[78:79]
	v_pk_fma_f32 v[114:115], v[164:165], v[4:5], v[114:115]
	v_pk_fma_f32 v[116:117], v[164:165], v[80:81], v[116:117]
	v_add_f32_e32 v122, v114, v115
	s_waitcnt lgkmcnt(10)
	v_pk_mul_f32 v[118:119], v[90:91], v[14:15] op_sel_hi:[0,1]
	v_add_f32_e32 v225, v116, v117
	v_add_f32_dpp v122, v122, v122 quad_perm:[1,0,3,2] row_mask:0xf bank_mask:0xf bound_ctrl:1
	v_pk_mul_f32 v[120:121], v[90:91], v[16:17] op_sel_hi:[0,1]
	ds_read_b128 v[74:77], v124 offset:19200
	v_add_f32_dpp v122, v122, v122 quad_perm:[2,3,0,1] row_mask:0xf bank_mask:0xf bound_ctrl:1
	v_pk_fma_f32 v[166:167], v[166:167], v[6:7], v[118:119]
	ds_read_b128 v[66:69], v124 offset:11008
	v_add_f32_dpp v122, v122, v122 row_half_mirror row_mask:0xf bank_mask:0xf bound_ctrl:1
	v_pk_fma_f32 v[164:165], v[164:165], v[8:9], v[120:121]
	ds_read_b128 v[70:73], v124 offset:35584
	v_add_f32_dpp v122, v122, v122 row_mirror row_mask:0xf bank_mask:0xf bound_ctrl:1
	v_add_f32_dpp v206, v210, v210 row_half_mirror row_mask:0xf bank_mask:0xa bound_ctrl:1
	v_add_f32_dpp v207, v211, v211 row_half_mirror row_mask:0xf bank_mask:0xa bound_ctrl:1
	v_pk_fma_f32 v[166:167], v[10:11], v[122:123], v[166:167] op_sel_hi:[1,0,1]
	v_pk_fma_f32 v[164:165], v[12:13], v[122:123], v[164:165] op_sel_hi:[1,0,1]
	ds_read_b128 v[78:81], v124 offset:2816
	ds_read_b128 v[62:65], v124 offset:27392
	s_waitcnt lgkmcnt(10)
; #define LAS __attribute__((address_space(3)))
; template <int CTRL> __device__ __forceinline__ float dpp_f(float x) { return __int_as_float(__builtin_amdgcn_update_dpp(0, __float_as_int(x), CTRL, 0xf, 0xf, false)); }
; __device__ __forceinline__ void phase_scan(const Params& p, LAS unsigned char* lds) {
;     ...
;                         for (int u16 = 0; u16 < 16; ++u16) {
;                             const int s = 16 * hb + u16;
;                             const int sn = (s + 1) & 31;
;                             const f32x4 a_n = *(const LAS f32x4*)(sA + sn * 64), w_n = *(const LAS f32x4*)(sW + sn * 64), b_n = *(const LAS f32x4*)(sB + sn * 64);
;                             const f32x4 k_n = *(const LAS f32x4*)(sK + sn * 64), r_n = *(const LAS f32x4*)(sR + sn * 64);
;                             const float v = vq[u16 >> 2][u16 & 3];
;                             const f32x2 vv = {v, v};
;                             f32x2 pp = S01 * (f32x2){a_[0], a_[1]}; pp = S23 * (f32x2){a_[2], a_[3]} + pp;
;                             f32x2 yy = S01 * (f32x2){rp[0], rp[1]}; yy = S23 * (f32x2){rp[2], rp[3]} + yy;
;                             float sa = pp[0] + pp[1], y = yy[0] + yy[1];
;                             sa += dpp_f<0xB1>(sa); y += dpp_f<0xB1>(y);
;                             sa += dpp_f<0x4E>(sa); y += dpp_f<0x4E>(y);
;                             sa += dpp_f<0x141>(sa); y += dpp_f<0x141>(y);
;                             sa += dpp_f<0x140>(sa); y += dpp_f<0x140>(y);
;                             sY[((s - 1) & 31) * 16 + srow] = y;
;                             const f32x2 sv = {sa, sa};
;                             S01 = S01 * (f32x2){w_[0], w_[1]} + vv * (f32x2){k_[0], k_[1]};
;                             S23 = S23 * (f32x2){w_[2], w_[3]} + vv * (f32x2){k_[2], k_[3]};
;                             S01 = sv * (f32x2){b_[0], b_[1]} + S01;
;                             S23 = sv * (f32x2){b_[2], b_[3]} + S23;
;                             rp = r_;
;                             a_ = a_n; w_ = w_n; b_ = b_n; k_ = k_n; r_ = r_n;
;                         }
	v_pk_mul_f32 v[114:115], v[166:167], v[22:23]
	v_pk_mul_f32 v[116:117], v[166:167], v[18:19]
	v_pk_fma_f32 v[114:115], v[164:165], v[24:25], v[114:115]
	v_pk_fma_f32 v[116:117], v[164:165], v[20:21], v[116:117]
	v_add_f32_e32 v122, v114, v115
	v_pk_mul_f32 v[118:119], v[90:91], v[34:35] op_sel:[1,0]
	v_add_f32_e32 v226, v116, v117
	v_add_f32_dpp v122, v122, v122 quad_perm:[1,0,3,2] row_mask:0xf bank_mask:0xf bound_ctrl:1
	v_pk_mul_f32 v[120:121], v[90:91], v[36:37] op_sel:[1,0]
	ds_read_b128 v[14:17], v124 offset:19456
	v_add_f32_dpp v122, v122, v122 quad_perm:[2,3,0,1] row_mask:0xf bank_mask:0xf bound_ctrl:1
	v_pk_fma_f32 v[166:167], v[166:167], v[26:27], v[118:119]
	ds_read_b128 v[6:9], v124 offset:11264
	v_add_f32_dpp v122, v122, v122 row_half_mirror row_mask:0xf bank_mask:0xf bound_ctrl:1
	v_pk_fma_f32 v[164:165], v[164:165], v[28:29], v[120:121]
	ds_read_b128 v[10:13], v124 offset:35840
	v_add_f32_dpp v122, v122, v122 row_mirror row_mask:0xf bank_mask:0xf bound_ctrl:1
	v_add_f32_dpp v204, v204, v204 quad_perm:[1,0,3,2] row_mask:0xf bank_mask:0xf bound_ctrl:1
	v_add_f32_dpp v205, v205, v205 quad_perm:[1,0,3,2] row_mask:0xf bank_mask:0xf bound_ctrl:1
	v_pk_fma_f32 v[166:167], v[30:31], v[122:123], v[166:167] op_sel_hi:[1,0,1]
	v_pk_fma_f32 v[164:165], v[32:33], v[122:123], v[164:165] op_sel_hi:[1,0,1]
	ds_read_b128 v[18:21], v124 offset:3072
	ds_read_b128 v[2:5], v124 offset:27648
	ds_read_b128 v[94:97], v125 offset:41008
	s_waitcnt lgkmcnt(11)
	v_pk_mul_f32 v[114:115], v[166:167], v[42:43]
	v_pk_mul_f32 v[116:117], v[166:167], v[38:39]
	v_pk_fma_f32 v[114:115], v[164:165], v[44:45], v[114:115]
	v_pk_fma_f32 v[116:117], v[164:165], v[40:41], v[116:117]
	v_add_f32_e32 v122, v114, v115
	v_pk_mul_f32 v[118:119], v[92:93], v[54:55] op_sel_hi:[0,1]
	v_add_f32_e32 v227, v116, v117
	v_add_f32_dpp v122, v122, v122 quad_perm:[1,0,3,2] row_mask:0xf bank_mask:0xf bound_ctrl:1
	v_pk_mul_f32 v[120:121], v[92:93], v[56:57] op_sel_hi:[0,1]
	ds_read_b128 v[34:37], v124 offset:19712
	v_add_f32_dpp v122, v122, v122 quad_perm:[2,3,0,1] row_mask:0xf bank_mask:0xf bound_ctrl:1
	v_pk_fma_f32 v[166:167], v[166:167], v[46:47], v[118:119]
	ds_read_b128 v[26:29], v124 offset:11520
	v_add_f32_dpp v122, v122, v122 row_half_mirror row_mask:0xf bank_mask:0xf bound_ctrl:1
	v_pk_fma_f32 v[164:165], v[164:165], v[48:49], v[120:121]
	ds_read_b128 v[30:33], v124 offset:36096
	v_add_f32_dpp v122, v122, v122 row_mirror row_mask:0xf bank_mask:0xf bound_ctrl:1
	v_add_f32_dpp v206, v206, v206 quad_perm:[1,0,3,2] row_mask:0xf bank_mask:0xf bound_ctrl:1
	v_add_f32_dpp v207, v207, v207 quad_perm:[1,0,3,2] row_mask:0xf bank_mask:0xf bound_ctrl:1
	v_pk_fma_f32 v[166:167], v[50:51], v[122:123], v[166:167] op_sel_hi:[1,0,1]
	v_pk_fma_f32 v[164:165], v[52:53], v[122:123], v[164:165] op_sel_hi:[1,0,1]
	ds_read_b128 v[38:41], v124 offset:3328
	ds_read_b128 v[22:25], v124 offset:27904
	s_waitcnt lgkmcnt(11)
	v_pk_mul_f32 v[114:115], v[166:167], v[62:63]
	v_pk_mul_f32 v[116:117], v[166:167], v[58:59]
	v_pk_fma_f32 v[114:115], v[164:165], v[64:65], v[114:115]
	v_pk_fma_f32 v[116:117], v[164:165], v[60:61], v[116:117]
	v_add_f32_e32 v122, v114, v115
	v_pk_mul_f32 v[118:119], v[92:93], v[74:75] op_sel:[1,0]
	v_add_f32_e32 v228, v116, v117
	v_add_f32_dpp v122, v122, v122 quad_perm:[1,0,3,2] row_mask:0xf bank_mask:0xf bound_ctrl:1
	v_pk_mul_f32 v[120:121], v[92:93], v[76:77] op_sel:[1,0]
	ds_read_b128 v[54:57], v124 offset:19968
	v_add_f32_dpp v122, v122, v122 quad_perm:[2,3,0,1] row_mask:0xf bank_mask:0xf bound_ctrl:1
	v_pk_fma_f32 v[166:167], v[166:167], v[66:67], v[118:119]
	ds_read_b128 v[46:49], v124 offset:11776
	v_add_f32_dpp v122, v122, v122 row_half_mirror row_mask:0xf bank_mask:0xf bound_ctrl:1
	v_pk_fma_f32 v[164:165], v[164:165], v[68:69], v[120:121]
	ds_read_b128 v[50:53], v124 offset:36352
	v_add_f32_dpp v122, v122, v122 row_mirror row_mask:0xf bank_mask:0xf bound_ctrl:1
	v_add_f32_dpp v204, v204, v204 quad_perm:[2,3,0,1] row_mask:0xf bank_mask:0xf bound_ctrl:1
	v_add_f32_dpp v205, v205, v205 quad_perm:[2,3,0,1] row_mask:0xf bank_mask:0xf bound_ctrl:1
	v_pk_fma_f32 v[166:167], v[70:71], v[122:123], v[166:167] op_sel_hi:[1,0,1]
	v_pk_fma_f32 v[164:165], v[72:73], v[122:123], v[164:165] op_sel_hi:[1,0,1]
	ds_read_b128 v[58:61], v124 offset:3584
	ds_read_b128 v[42:45], v124 offset:28160
	s_waitcnt lgkmcnt(11)
	v_pk_mul_f32 v[114:115], v[166:167], v[2:3]
	v_pk_mul_f32 v[116:117], v[166:167], v[78:79]
	v_pk_fma_f32 v[114:115], v[164:165], v[4:5], v[114:115]
	v_pk_fma_f32 v[116:117], v[164:165], v[80:81], v[116:117]
	v_add_f32_e32 v122, v114, v115
	s_waitcnt lgkmcnt(10)
	v_pk_mul_f32 v[118:119], v[94:95], v[14:15] op_sel_hi:[0,1]
	v_add_f32_e32 v229, v116, v117
	v_add_f32_dpp v122, v122, v122 quad_perm:[1,0,3,2] row_mask:0xf bank_mask:0xf bound_ctrl:1
	v_pk_mul_f32 v[120:121], v[94:95], v[16:17] op_sel_hi:[0,1]
	ds_read_b128 v[74:77], v124 offset:20224
	v_add_f32_dpp v122, v122, v122 quad_perm:[2,3,0,1] row_mask:0xf bank_mask:0xf bound_ctrl:1
	v_pk_fma_f32 v[166:167], v[166:167], v[6:7], v[118:119]
	ds_read_b128 v[66:69], v124 offset:12032
	v_add_f32_dpp v122, v122, v122 row_half_mirror row_mask:0xf bank_mask:0xf bound_ctrl:1
	v_pk_fma_f32 v[164:165], v[164:165], v[8:9], v[120:121]
	ds_read_b128 v[70:73], v124 offset:36608
	v_add_f32_dpp v122, v122, v122 row_mirror row_mask:0xf bank_mask:0xf bound_ctrl:1
	v_add_f32_dpp v206, v206, v206 quad_perm:[2,3,0,1] row_mask:0xf bank_mask:0xf bound_ctrl:1
	v_add_f32_dpp v207, v207, v207 quad_perm:[2,3,0,1] row_mask:0xf bank_mask:0xf bound_ctrl:1
	v_pk_fma_f32 v[166:167], v[10:11], v[122:123], v[166:167] op_sel_hi:[1,0,1]
	v_pk_fma_f32 v[164:165], v[12:13], v[122:123], v[164:165] op_sel_hi:[1,0,1]
	ds_read_b128 v[78:81], v124 offset:3840
	ds_read_b128 v[62:65], v124 offset:28416
	s_waitcnt lgkmcnt(10)
; #define LAS __attribute__((address_space(3)))
; template <int CTRL> __device__ __forceinline__ float dpp_f(float x) { return __int_as_float(__builtin_amdgcn_update_dpp(0, __float_as_int(x), CTRL, 0xf, 0xf, false)); }
; __device__ __forceinline__ void phase_scan(const Params& p, LAS unsigned char* lds) {
;     ...
;                         for (int u16 = 0; u16 < 16; ++u16) {
;                             const int s = 16 * hb + u16;
;                             const int sn = (s + 1) & 31;
;                             const f32x4 a_n = *(const LAS f32x4*)(sA + sn * 64), w_n = *(const LAS f32x4*)(sW + sn * 64), b_n = *(const LAS f32x4*)(sB + sn * 64);
;                             const f32x4 k_n = *(const LAS f32x4*)(sK + sn * 64), r_n = *(const LAS f32x4*)(sR + sn * 64);
;                             const float v = vq[u16 >> 2][u16 & 3];
;                             const f32x2 vv = {v, v};
;                             f32x2 pp = S01 * (f32x2){a_[0], a_[1]}; pp = S23 * (f32x2){a_[2], a_[3]} + pp;
;                             f32x2 yy = S01 * (f32x2){rp[0], rp[1]}; yy = S23 * (f32x2){rp[2], rp[3]} + yy;
;                             float sa = pp[0] + pp[1], y = yy[0] + yy[1];
;                             sa += dpp_f<0xB1>(sa); y += dpp_f<0xB1>(y);
;                             sa += dpp_f<0x4E>(sa); y += dpp_f<0x4E>(y);
;                             sa += dpp_f<0x141>(sa); y += dpp_f<0x141>(y);
;                             sa += dpp_f<0x140>(sa); y += dpp_f<0x140>(y);
;                             sY[((s - 1) & 31) * 16 + srow] = y;
;                             const f32x2 sv = {sa, sa};
;                             S01 = S01 * (f32x2){w_[0], w_[1]} + vv * (f32x2){k_[0], k_[1]};
;                             S23 = S23 * (f32x2){w_[2], w_[3]} + vv * (f32x2){k_[2], k_[3]};
;                             S01 = sv * (f32x2){b_[0], b_[1]} + S01;
;                             S23 = sv * (f32x2){b_[2], b_[3]} + S23;
;                             rp = r_;
;                             a_ = a_n; w_ = w_n; b_ = b_n; k_ = k_n; r_ = r_n;
;                         }
	v_pk_mul_f32 v[114:115], v[166:167], v[22:23]
	v_pk_mul_f32 v[116:117], v[166:167], v[18:19]
	v_pk_fma_f32 v[114:115], v[164:165], v[24:25], v[114:115]
	v_pk_fma_f32 v[116:117], v[164:165], v[20:21], v[116:117]
	v_add_f32_e32 v122, v114, v115
	v_pk_mul_f32 v[118:119], v[94:95], v[34:35] op_sel:[1,0]
	v_add_f32_e32 v230, v116, v117
	v_add_f32_dpp v122, v122, v122 quad_perm:[1,0,3,2] row_mask:0xf bank_mask:0xf bound_ctrl:1
	v_pk_mul_f32 v[120:121], v[94:95], v[36:37] op_sel:[1,0]
	ds_read_b128 v[14:17], v124 offset:20480
	v_add_f32_dpp v122, v122, v122 quad_perm:[2,3,0,1] row_mask:0xf bank_mask:0xf bound_ctrl:1
	v_pk_fma_f32 v[166:167], v[166:167], v[26:27], v[118:119]
	ds_read_b128 v[6:9], v124 offset:12288
	v_add_f32_dpp v122, v122, v122 row_half_mirror row_mask:0xf bank_mask:0xf bound_ctrl:1
	v_pk_fma_f32 v[164:165], v[164:165], v[28:29], v[120:121]
	ds_read_b128 v[10:13], v124 offset:36864
	v_add_f32_dpp v122, v122, v122 row_mirror row_mask:0xf bank_mask:0xf bound_ctrl:1
	v_cndmask_b32_e64 v202, v204, v205, s[34:35]
	v_cndmask_b32_e64 v202, v202, v206, s[56:57]
	v_pk_fma_f32 v[166:167], v[30:31], v[122:123], v[166:167] op_sel_hi:[1,0,1]
	v_pk_fma_f32 v[164:165], v[32:33], v[122:123], v[164:165] op_sel_hi:[1,0,1]
	ds_read_b128 v[18:21], v124 offset:4096
	ds_read_b128 v[2:5], v124 offset:28672
	ds_read_b128 v[98:101], v125 offset:41024
	s_waitcnt lgkmcnt(11)
	v_pk_mul_f32 v[114:115], v[166:167], v[42:43]
	v_pk_mul_f32 v[116:117], v[166:167], v[38:39]
	v_pk_fma_f32 v[114:115], v[164:165], v[44:45], v[114:115]
	v_pk_fma_f32 v[116:117], v[164:165], v[40:41], v[116:117]
	v_add_f32_e32 v122, v114, v115
	v_pk_mul_f32 v[118:119], v[96:97], v[54:55] op_sel_hi:[0,1]
	v_add_f32_e32 v231, v116, v117
	v_add_f32_dpp v122, v122, v122 quad_perm:[1,0,3,2] row_mask:0xf bank_mask:0xf bound_ctrl:1
	v_pk_mul_f32 v[120:121], v[96:97], v[56:57] op_sel_hi:[0,1]
	ds_read_b128 v[34:37], v124 offset:20736
	v_add_f32_dpp v122, v122, v122 quad_perm:[2,3,0,1] row_mask:0xf bank_mask:0xf bound_ctrl:1
	v_pk_fma_f32 v[166:167], v[166:167], v[46:47], v[118:119]
	ds_read_b128 v[26:29], v124 offset:12544
	v_add_f32_dpp v122, v122, v122 row_half_mirror row_mask:0xf bank_mask:0xf bound_ctrl:1
	v_pk_fma_f32 v[164:165], v[164:165], v[48:49], v[120:121]
	ds_read_b128 v[30:33], v124 offset:37120
	v_add_f32_dpp v122, v122, v122 row_mirror row_mask:0xf bank_mask:0xf bound_ctrl:1
	v_cndmask_b32_e64 v202, v202, v207, s[98:99]
	v_cvt_f16_f32_e32 v203, v202
	v_pk_fma_f32 v[166:167], v[50:51], v[122:123], v[166:167] op_sel_hi:[1,0,1]
	v_pk_fma_f32 v[164:165], v[52:53], v[122:123], v[164:165] op_sel_hi:[1,0,1]
	ds_read_b128 v[38:41], v124 offset:4352
	ds_read_b128 v[22:25], v124 offset:28928
	s_waitcnt lgkmcnt(11)
	v_pk_mul_f32 v[114:115], v[166:167], v[62:63]
	v_pk_mul_f32 v[116:117], v[166:167], v[58:59]
	v_pk_fma_f32 v[114:115], v[164:165], v[64:65], v[114:115]
	v_pk_fma_f32 v[116:117], v[164:165], v[60:61], v[116:117]
	v_add_f32_e32 v122, v114, v115
	v_pk_mul_f32 v[118:119], v[96:97], v[74:75] op_sel:[1,0]
	v_add_f32_e32 v232, v116, v117
	v_add_f32_dpp v122, v122, v122 quad_perm:[1,0,3,2] row_mask:0xf bank_mask:0xf bound_ctrl:1
	v_pk_mul_f32 v[120:121], v[96:97], v[76:77] op_sel:[1,0]
	ds_read_b128 v[54:57], v124 offset:20992
	v_add_f32_dpp v122, v122, v122 quad_perm:[2,3,0,1] row_mask:0xf bank_mask:0xf bound_ctrl:1
	v_pk_fma_f32 v[166:167], v[166:167], v[66:67], v[118:119]
	ds_read_b128 v[46:49], v124 offset:12800
	v_add_f32_dpp v122, v122, v122 row_half_mirror row_mask:0xf bank_mask:0xf bound_ctrl:1
	v_pk_fma_f32 v[164:165], v[164:165], v[68:69], v[120:121]
	ds_read_b128 v[50:53], v124 offset:37376
	v_add_f32_dpp v122, v122, v122 row_mirror row_mask:0xf bank_mask:0xf bound_ctrl:1
	s_mov_b64 exec, s[14:15]
	global_store_short v[128:129], v203, off
	s_mov_b64 exec, -1
	v_lshl_add_u64 v[128:129], v[128:129], 0, s[100:101]
	v_pk_fma_f32 v[166:167], v[70:71], v[122:123], v[166:167] op_sel_hi:[1,0,1]
	v_pk_fma_f32 v[164:165], v[72:73], v[122:123], v[164:165] op_sel_hi:[1,0,1]
	ds_read_b128 v[58:61], v124 offset:4608
	ds_read_b128 v[42:45], v124 offset:29184
	s_waitcnt lgkmcnt(11)
	v_pk_mul_f32 v[114:115], v[166:167], v[2:3]
	v_pk_mul_f32 v[116:117], v[166:167], v[78:79]
	v_pk_fma_f32 v[114:115], v[164:165], v[4:5], v[114:115]
	v_pk_fma_f32 v[116:117], v[164:165], v[80:81], v[116:117]
	v_add_f32_e32 v122, v114, v115
	s_waitcnt lgkmcnt(10)
	v_pk_mul_f32 v[118:119], v[98:99], v[14:15] op_sel_hi:[0,1]
	v_add_f32_e32 v233, v116, v117
	v_add_f32_dpp v122, v122, v122 quad_perm:[1,0,3,2] row_mask:0xf bank_mask:0xf bound_ctrl:1
	v_pk_mul_f32 v[120:121], v[98:99], v[16:17] op_sel_hi:[0,1]
	ds_read_b128 v[74:77], v124 offset:21248
	v_add_f32_dpp v122, v122, v122 quad_perm:[2,3,0,1] row_mask:0xf bank_mask:0xf bound_ctrl:1
	v_pk_fma_f32 v[166:167], v[166:167], v[6:7], v[118:119]
	ds_read_b128 v[66:69], v124 offset:13056
	v_add_f32_dpp v122, v122, v122 row_half_mirror row_mask:0xf bank_mask:0xf bound_ctrl:1
	v_pk_fma_f32 v[164:165], v[164:165], v[8:9], v[120:121]
	ds_read_b128 v[70:73], v124 offset:37632
	v_add_f32_dpp v122, v122, v122 row_mirror row_mask:0xf bank_mask:0xf bound_ctrl:1
	v_add_f32_dpp v220, v220, v220 row_mirror row_mask:0xf bank_mask:0xf bound_ctrl:1
	v_add_f32_dpp v220, v228, v228 row_mirror row_mask:0xf bank_mask:0xc bound_ctrl:1
	v_pk_fma_f32 v[166:167], v[10:11], v[122:123], v[166:167] op_sel_hi:[1,0,1]
	v_pk_fma_f32 v[164:165], v[12:13], v[122:123], v[164:165] op_sel_hi:[1,0,1]
	ds_read_b128 v[78:81], v124 offset:4864
	ds_read_b128 v[62:65], v124 offset:29440
	s_waitcnt lgkmcnt(10)
; #define LAS __attribute__((address_space(3)))
; template <int CTRL> __device__ __forceinline__ float dpp_f(float x) { return __int_as_float(__builtin_amdgcn_update_dpp(0, __float_as_int(x), CTRL, 0xf, 0xf, false)); }
; __device__ __forceinline__ void phase_scan(const Params& p, LAS unsigned char* lds) {
;     ...
;                         for (int u16 = 0; u16 < 16; ++u16) {
;                             const int s = 16 * hb + u16;
;                             const int sn = (s + 1) & 31;
;                             const f32x4 a_n = *(const LAS f32x4*)(sA + sn * 64), w_n = *(const LAS f32x4*)(sW + sn * 64), b_n = *(const LAS f32x4*)(sB + sn * 64);
;                             const f32x4 k_n = *(const LAS f32x4*)(sK + sn * 64), r_n = *(const LAS f32x4*)(sR + sn * 64);
;                             const float v = vq[u16 >> 2][u16 & 3];
;                             const f32x2 vv = {v, v};
;                             f32x2 pp = S01 * (f32x2){a_[0], a_[1]}; pp = S23 * (f32x2){a_[2], a_[3]} + pp;
;                             f32x2 yy = S01 * (f32x2){rp[0], rp[1]}; yy = S23 * (f32x2){rp[2], rp[3]} + yy;
;                             float sa = pp[0] + pp[1], y = yy[0] + yy[1];
;                             sa += dpp_f<0xB1>(sa); y += dpp_f<0xB1>(y);
;                             sa += dpp_f<0x4E>(sa); y += dpp_f<0x4E>(y);
;                             sa += dpp_f<0x141>(sa); y += dpp_f<0x141>(y);
;                             sa += dpp_f<0x140>(sa); y += dpp_f<0x140>(y);
;                             sY[((s - 1) & 31) * 16 + srow] = y;
;                             const f32x2 sv = {sa, sa};
;                             S01 = S01 * (f32x2){w_[0], w_[1]} + vv * (f32x2){k_[0], k_[1]};
;                             S23 = S23 * (f32x2){w_[2], w_[3]} + vv * (f32x2){k_[2], k_[3]};
;                             S01 = sv * (f32x2){b_[0], b_[1]} + S01;
;                             S23 = sv * (f32x2){b_[2], b_[3]} + S23;
;                             rp = r_;
;                             a_ = a_n; w_ = w_n; b_ = b_n; k_ = k_n; r_ = r_n;
;                         }
	v_pk_mul_f32 v[114:115], v[166:167], v[22:23]
	v_pk_mul_f32 v[116:117], v[166:167], v[18:19]
	v_pk_fma_f32 v[114:115], v[164:165], v[24:25], v[114:115]
	v_pk_fma_f32 v[116:117], v[164:165], v[20:21], v[116:117]
	v_add_f32_e32 v122, v114, v115
	v_pk_mul_f32 v[118:119], v[98:99], v[34:35] op_sel:[1,0]
	v_add_f32_e32 v234, v116, v117
	v_add_f32_dpp v122, v122, v122 quad_perm:[1,0,3,2] row_mask:0xf bank_mask:0xf bound_ctrl:1
	v_pk_mul_f32 v[120:121], v[98:99], v[36:37] op_sel:[1,0]
	ds_read_b128 v[14:17], v124 offset:21504
	v_add_f32_dpp v122, v122, v122 quad_perm:[2,3,0,1] row_mask:0xf bank_mask:0xf bound_ctrl:1
	v_pk_fma_f32 v[166:167], v[166:167], v[26:27], v[118:119]
	ds_read_b128 v[6:9], v124 offset:13312
	v_add_f32_dpp v122, v122, v122 row_half_mirror row_mask:0xf bank_mask:0xf bound_ctrl:1
	v_pk_fma_f32 v[164:165], v[164:165], v[28:29], v[120:121]
	ds_read_b128 v[10:13], v124 offset:37888
	v_add_f32_dpp v122, v122, v122 row_mirror row_mask:0xf bank_mask:0xf bound_ctrl:1
	v_add_f32_dpp v221, v221, v221 row_mirror row_mask:0xf bank_mask:0xf bound_ctrl:1
	v_add_f32_dpp v221, v229, v229 row_mirror row_mask:0xf bank_mask:0xc bound_ctrl:1
	v_pk_fma_f32 v[166:167], v[30:31], v[122:123], v[166:167] op_sel_hi:[1,0,1]
	v_pk_fma_f32 v[164:165], v[32:33], v[122:123], v[164:165] op_sel_hi:[1,0,1]
	ds_read_b128 v[18:21], v124 offset:5120
	ds_read_b128 v[2:5], v124 offset:29696
	ds_read_b128 v[102:105], v125 offset:41040
	s_waitcnt lgkmcnt(11)
	v_pk_mul_f32 v[114:115], v[166:167], v[42:43]
	v_pk_mul_f32 v[116:117], v[166:167], v[38:39]
	v_pk_fma_f32 v[114:115], v[164:165], v[44:45], v[114:115]
	v_pk_fma_f32 v[116:117], v[164:165], v[40:41], v[116:117]
	v_add_f32_e32 v122, v114, v115
	v_pk_mul_f32 v[118:119], v[100:101], v[54:55] op_sel_hi:[0,1]
	v_add_f32_e32 v235, v116, v117
	v_add_f32_dpp v122, v122, v122 quad_perm:[1,0,3,2] row_mask:0xf bank_mask:0xf bound_ctrl:1
	v_pk_mul_f32 v[120:121], v[100:101], v[56:57] op_sel_hi:[0,1]
	ds_read_b128 v[34:37], v124 offset:21760
	v_add_f32_dpp v122, v122, v122 quad_perm:[2,3,0,1] row_mask:0xf bank_mask:0xf bound_ctrl:1
	v_pk_fma_f32 v[166:167], v[166:167], v[46:47], v[118:119]
	ds_read_b128 v[26:29], v124 offset:13568
	v_add_f32_dpp v122, v122, v122 row_half_mirror row_mask:0xf bank_mask:0xf bound_ctrl:1
	v_pk_fma_f32 v[164:165], v[164:165], v[48:49], v[120:121]
	ds_read_b128 v[30:33], v124 offset:38144
	v_add_f32_dpp v122, v122, v122 row_mirror row_mask:0xf bank_mask:0xf bound_ctrl:1
	v_add_f32_dpp v222, v222, v222 row_mirror row_mask:0xf bank_mask:0xf bound_ctrl:1
	v_add_f32_dpp v222, v230, v230 row_mirror row_mask:0xf bank_mask:0xc bound_ctrl:1
	v_pk_fma_f32 v[166:167], v[50:51], v[122:123], v[166:167] op_sel_hi:[1,0,1]
	v_pk_fma_f32 v[164:165], v[52:53], v[122:123], v[164:165] op_sel_hi:[1,0,1]
	ds_read_b128 v[38:41], v124 offset:5376
	ds_read_b128 v[22:25], v124 offset:29952
	s_waitcnt lgkmcnt(11)
	v_pk_mul_f32 v[114:115], v[166:167], v[62:63]
	v_pk_mul_f32 v[116:117], v[166:167], v[58:59]
	v_pk_fma_f32 v[114:115], v[164:165], v[64:65], v[114:115]
	v_pk_fma_f32 v[116:117], v[164:165], v[60:61], v[116:117]
	v_add_f32_e32 v122, v114, v115
	v_pk_mul_f32 v[118:119], v[100:101], v[74:75] op_sel:[1,0]
	v_add_f32_e32 v204, v116, v117
	v_add_f32_dpp v122, v122, v122 quad_perm:[1,0,3,2] row_mask:0xf bank_mask:0xf bound_ctrl:1
	v_pk_mul_f32 v[120:121], v[100:101], v[76:77] op_sel:[1,0]
	ds_read_b128 v[54:57], v124 offset:22016
	v_add_f32_dpp v122, v122, v122 quad_perm:[2,3,0,1] row_mask:0xf bank_mask:0xf bound_ctrl:1
	v_pk_fma_f32 v[166:167], v[166:167], v[66:67], v[118:119]
	ds_read_b128 v[46:49], v124 offset:13824
	v_add_f32_dpp v122, v122, v122 row_half_mirror row_mask:0xf bank_mask:0xf bound_ctrl:1
	v_pk_fma_f32 v[164:165], v[164:165], v[68:69], v[120:121]
	ds_read_b128 v[50:53], v124 offset:38400
	v_add_f32_dpp v122, v122, v122 row_mirror row_mask:0xf bank_mask:0xf bound_ctrl:1
	v_add_f32_dpp v223, v223, v223 row_mirror row_mask:0xf bank_mask:0xf bound_ctrl:1
	v_add_f32_dpp v223, v231, v231 row_mirror row_mask:0xf bank_mask:0xc bound_ctrl:1
	v_pk_fma_f32 v[166:167], v[70:71], v[122:123], v[166:167] op_sel_hi:[1,0,1]
	v_pk_fma_f32 v[164:165], v[72:73], v[122:123], v[164:165] op_sel_hi:[1,0,1]
	ds_read_b128 v[58:61], v124 offset:5632
	ds_read_b128 v[42:45], v124 offset:30208
	s_waitcnt lgkmcnt(11)
	v_pk_mul_f32 v[114:115], v[166:167], v[2:3]
	v_pk_mul_f32 v[116:117], v[166:167], v[78:79]
	v_pk_fma_f32 v[114:115], v[164:165], v[4:5], v[114:115]
	v_pk_fma_f32 v[116:117], v[164:165], v[80:81], v[116:117]
	v_add_f32_e32 v122, v114, v115
	s_waitcnt lgkmcnt(10)
	v_pk_mul_f32 v[118:119], v[102:103], v[14:15] op_sel_hi:[0,1]
	v_add_f32_e32 v205, v116, v117
	v_add_f32_dpp v122, v122, v122 quad_perm:[1,0,3,2] row_mask:0xf bank_mask:0xf bound_ctrl:1
	v_pk_mul_f32 v[120:121], v[102:103], v[16:17] op_sel_hi:[0,1]
	ds_read_b128 v[74:77], v124 offset:22272
	v_add_f32_dpp v122, v122, v122 quad_perm:[2,3,0,1] row_mask:0xf bank_mask:0xf bound_ctrl:1
	v_pk_fma_f32 v[166:167], v[166:167], v[6:7], v[118:119]
	ds_read_b128 v[66:69], v124 offset:14080
	v_add_f32_dpp v122, v122, v122 row_half_mirror row_mask:0xf bank_mask:0xf bound_ctrl:1
	v_pk_fma_f32 v[164:165], v[164:165], v[8:9], v[120:121]
	ds_read_b128 v[70:73], v124 offset:38656
	v_add_f32_dpp v122, v122, v122 row_mirror row_mask:0xf bank_mask:0xf bound_ctrl:1
	v_add_f32_dpp v224, v224, v224 row_mirror row_mask:0xf bank_mask:0xf bound_ctrl:1
	v_add_f32_dpp v224, v232, v232 row_mirror row_mask:0xf bank_mask:0xc bound_ctrl:1
	v_pk_fma_f32 v[166:167], v[10:11], v[122:123], v[166:167] op_sel_hi:[1,0,1]
	v_pk_fma_f32 v[164:165], v[12:13], v[122:123], v[164:165] op_sel_hi:[1,0,1]
	ds_read_b128 v[78:81], v124 offset:5888
	ds_read_b128 v[62:65], v124 offset:30464
	s_waitcnt lgkmcnt(10)
; #define LAS __attribute__((address_space(3)))
; template <int CTRL> __device__ __forceinline__ float dpp_f(float x) { return __int_as_float(__builtin_amdgcn_update_dpp(0, __float_as_int(x), CTRL, 0xf, 0xf, false)); }
; __device__ __forceinline__ void phase_scan(const Params& p, LAS unsigned char* lds) {
;     ...
;                         for (int u16 = 0; u16 < 16; ++u16) {
;                             const int s = 16 * hb + u16;
;                             const int sn = (s + 1) & 31;
;                             const f32x4 a_n = *(const LAS f32x4*)(sA + sn * 64), w_n = *(const LAS f32x4*)(sW + sn * 64), b_n = *(const LAS f32x4*)(sB + sn * 64);
;                             const f32x4 k_n = *(const LAS f32x4*)(sK + sn * 64), r_n = *(const LAS f32x4*)(sR + sn * 64);
;                             const float v = vq[u16 >> 2][u16 & 3];
;                             const f32x2 vv = {v, v};
;                             f32x2 pp = S01 * (f32x2){a_[0], a_[1]}; pp = S23 * (f32x2){a_[2], a_[3]} + pp;
;                             f32x2 yy = S01 * (f32x2){rp[0], rp[1]}; yy = S23 * (f32x2){rp[2], rp[3]} + yy;
;                             float sa = pp[0] + pp[1], y = yy[0] + yy[1];
;                             sa += dpp_f<0xB1>(sa); y += dpp_f<0xB1>(y);
;                             sa += dpp_f<0x4E>(sa); y += dpp_f<0x4E>(y);
;                             sa += dpp_f<0x141>(sa); y += dpp_f<0x141>(y);
;                             sa += dpp_f<0x140>(sa); y += dpp_f<0x140>(y);
;                             sY[((s - 1) & 31) * 16 + srow] = y;
;                             const f32x2 sv = {sa, sa};
;                             S01 = S01 * (f32x2){w_[0], w_[1]} + vv * (f32x2){k_[0], k_[1]};
;                             S23 = S23 * (f32x2){w_[2], w_[3]} + vv * (f32x2){k_[2], k_[3]};
;                             S01 = sv * (f32x2){b_[0], b_[1]} + S01;
;                             S23 = sv * (f32x2){b_[2], b_[3]} + S23;
;                             rp = r_;
;                             a_ = a_n; w_ = w_n; b_ = b_n; k_ = k_n; r_ = r_n;
;                         }
	v_pk_mul_f32 v[114:115], v[166:167], v[22:23]
	v_pk_mul_f32 v[116:117], v[166:167], v[18:19]
	v_pk_fma_f32 v[114:115], v[164:165], v[24:25], v[114:115]
	v_pk_fma_f32 v[116:117], v[164:165], v[20:21], v[116:117]
	v_add_f32_e32 v122, v114, v115
	v_pk_mul_f32 v[118:119], v[102:103], v[34:35] op_sel:[1,0]
	v_add_f32_e32 v206, v116, v117
	v_add_f32_dpp v122, v122, v122 quad_perm:[1,0,3,2] row_mask:0xf bank_mask:0xf bound_ctrl:1
	v_pk_mul_f32 v[120:121], v[102:103], v[36:37] op_sel:[1,0]
	ds_read_b128 v[14:17], v124 offset:22528
	v_add_f32_dpp v122, v122, v122 quad_perm:[2,3,0,1] row_mask:0xf bank_mask:0xf bound_ctrl:1
	v_pk_fma_f32 v[166:167], v[166:167], v[26:27], v[118:119]
	ds_read_b128 v[6:9], v124 offset:14336
	v_add_f32_dpp v122, v122, v122 row_half_mirror row_mask:0xf bank_mask:0xf bound_ctrl:1
	v_pk_fma_f32 v[164:165], v[164:165], v[28:29], v[120:121]
	ds_read_b128 v[10:13], v124 offset:38912
	v_add_f32_dpp v122, v122, v122 row_mirror row_mask:0xf bank_mask:0xf bound_ctrl:1
	v_add_f32_dpp v225, v225, v225 row_mirror row_mask:0xf bank_mask:0xf bound_ctrl:1
	v_add_f32_dpp v225, v233, v233 row_mirror row_mask:0xf bank_mask:0xc bound_ctrl:1
	v_pk_fma_f32 v[166:167], v[30:31], v[122:123], v[166:167] op_sel_hi:[1,0,1]
	v_pk_fma_f32 v[164:165], v[32:33], v[122:123], v[164:165] op_sel_hi:[1,0,1]
	ds_read_b128 v[18:21], v124 offset:6144
	ds_read_b128 v[2:5], v124 offset:30720
	ds_read_b128 v[106:109], v125 offset:41056
	s_waitcnt lgkmcnt(11)
	v_pk_mul_f32 v[114:115], v[166:167], v[42:43]
	v_pk_mul_f32 v[116:117], v[166:167], v[38:39]
	v_pk_fma_f32 v[114:115], v[164:165], v[44:45], v[114:115]
	v_pk_fma_f32 v[116:117], v[164:165], v[40:41], v[116:117]
	v_add_f32_e32 v122, v114, v115
	v_pk_mul_f32 v[118:119], v[104:105], v[54:55] op_sel_hi:[0,1]
	v_add_f32_e32 v207, v116, v117
	v_add_f32_dpp v122, v122, v122 quad_perm:[1,0,3,2] row_mask:0xf bank_mask:0xf bound_ctrl:1
	v_pk_mul_f32 v[120:121], v[104:105], v[56:57] op_sel_hi:[0,1]
	ds_read_b128 v[34:37], v124 offset:22784
	v_add_f32_dpp v122, v122, v122 quad_perm:[2,3,0,1] row_mask:0xf bank_mask:0xf bound_ctrl:1
	v_pk_fma_f32 v[166:167], v[166:167], v[46:47], v[118:119]
	ds_read_b128 v[26:29], v124 offset:14592
	v_add_f32_dpp v122, v122, v122 row_half_mirror row_mask:0xf bank_mask:0xf bound_ctrl:1
	v_pk_fma_f32 v[164:165], v[164:165], v[48:49], v[120:121]
	ds_read_b128 v[30:33], v124 offset:39168
	v_add_f32_dpp v122, v122, v122 row_mirror row_mask:0xf bank_mask:0xf bound_ctrl:1
	v_add_f32_dpp v226, v226, v226 row_mirror row_mask:0xf bank_mask:0xf bound_ctrl:1
	v_add_f32_dpp v226, v234, v234 row_mirror row_mask:0xf bank_mask:0xc bound_ctrl:1
	v_pk_fma_f32 v[166:167], v[50:51], v[122:123], v[166:167] op_sel_hi:[1,0,1]
	v_pk_fma_f32 v[164:165], v[52:53], v[122:123], v[164:165] op_sel_hi:[1,0,1]
	ds_read_b128 v[38:41], v124 offset:6400
	ds_read_b128 v[22:25], v124 offset:30976
	s_waitcnt lgkmcnt(11)
	v_pk_mul_f32 v[114:115], v[166:167], v[62:63]
	v_pk_mul_f32 v[116:117], v[166:167], v[58:59]
	v_pk_fma_f32 v[114:115], v[164:165], v[64:65], v[114:115]
	v_pk_fma_f32 v[116:117], v[164:165], v[60:61], v[116:117]
	v_add_f32_e32 v122, v114, v115
	v_pk_mul_f32 v[118:119], v[104:105], v[74:75] op_sel:[1,0]
	v_add_f32_e32 v208, v116, v117
	v_add_f32_dpp v122, v122, v122 quad_perm:[1,0,3,2] row_mask:0xf bank_mask:0xf bound_ctrl:1
	v_pk_mul_f32 v[120:121], v[104:105], v[76:77] op_sel:[1,0]
	ds_read_b128 v[54:57], v124 offset:23040
	v_add_f32_dpp v122, v122, v122 quad_perm:[2,3,0,1] row_mask:0xf bank_mask:0xf bound_ctrl:1
	v_pk_fma_f32 v[166:167], v[166:167], v[66:67], v[118:119]
	ds_read_b128 v[46:49], v124 offset:14848
	v_add_f32_dpp v122, v122, v122 row_half_mirror row_mask:0xf bank_mask:0xf bound_ctrl:1
	v_pk_fma_f32 v[164:165], v[164:165], v[68:69], v[120:121]
	ds_read_b128 v[50:53], v124 offset:39424
	v_add_f32_dpp v122, v122, v122 row_mirror row_mask:0xf bank_mask:0xf bound_ctrl:1
	v_add_f32_dpp v227, v227, v227 row_mirror row_mask:0xf bank_mask:0xf bound_ctrl:1
	v_add_f32_dpp v227, v235, v235 row_mirror row_mask:0xf bank_mask:0xc bound_ctrl:1
	v_pk_fma_f32 v[166:167], v[70:71], v[122:123], v[166:167] op_sel_hi:[1,0,1]
	v_pk_fma_f32 v[164:165], v[72:73], v[122:123], v[164:165] op_sel_hi:[1,0,1]
	ds_read_b128 v[58:61], v124 offset:6656
	ds_read_b128 v[42:45], v124 offset:31232
	s_waitcnt lgkmcnt(11)
	v_pk_mul_f32 v[114:115], v[166:167], v[2:3]
	v_pk_mul_f32 v[116:117], v[166:167], v[78:79]
	v_pk_fma_f32 v[114:115], v[164:165], v[4:5], v[114:115]
	v_pk_fma_f32 v[116:117], v[164:165], v[80:81], v[116:117]
	v_add_f32_e32 v122, v114, v115
	s_waitcnt lgkmcnt(10)
	v_pk_mul_f32 v[118:119], v[106:107], v[14:15] op_sel_hi:[0,1]
	v_add_f32_e32 v209, v116, v117
	v_add_f32_dpp v122, v122, v122 quad_perm:[1,0,3,2] row_mask:0xf bank_mask:0xf bound_ctrl:1
	v_pk_mul_f32 v[120:121], v[106:107], v[16:17] op_sel_hi:[0,1]
	ds_read_b128 v[74:77], v124 offset:23296
	v_add_f32_dpp v122, v122, v122 quad_perm:[2,3,0,1] row_mask:0xf bank_mask:0xf bound_ctrl:1
	v_pk_fma_f32 v[166:167], v[166:167], v[6:7], v[118:119]
	ds_read_b128 v[66:69], v124 offset:15104
	v_add_f32_dpp v122, v122, v122 row_half_mirror row_mask:0xf bank_mask:0xf bound_ctrl:1
	v_pk_fma_f32 v[164:165], v[164:165], v[8:9], v[120:121]
	ds_read_b128 v[70:73], v124 offset:39680
	v_add_f32_dpp v122, v122, v122 row_mirror row_mask:0xf bank_mask:0xf bound_ctrl:1
	v_add_f32_dpp v220, v220, v220 row_half_mirror row_mask:0xf bank_mask:0xf bound_ctrl:1
	v_add_f32_dpp v221, v221, v221 row_half_mirror row_mask:0xf bank_mask:0xf bound_ctrl:1
	v_pk_fma_f32 v[166:167], v[10:11], v[122:123], v[166:167] op_sel_hi:[1,0,1]
	v_pk_fma_f32 v[164:165], v[12:13], v[122:123], v[164:165] op_sel_hi:[1,0,1]
	ds_read_b128 v[78:81], v124 offset:6912
	ds_read_b128 v[62:65], v124 offset:31488
	s_waitcnt lgkmcnt(10)
; #define LAS __attribute__((address_space(3)))
; template <int CTRL> __device__ __forceinline__ float dpp_f(float x) { return __int_as_float(__builtin_amdgcn_update_dpp(0, __float_as_int(x), CTRL, 0xf, 0xf, false)); }
; __device__ __forceinline__ void phase_scan(const Params& p, LAS unsigned char* lds) {
;     ...
;                         for (int u16 = 0; u16 < 16; ++u16) {
;                             const int s = 16 * hb + u16;
;                             const int sn = (s + 1) & 31;
;                             const f32x4 a_n = *(const LAS f32x4*)(sA + sn * 64), w_n = *(const LAS f32x4*)(sW + sn * 64), b_n = *(const LAS f32x4*)(sB + sn * 64);
;                             const f32x4 k_n = *(const LAS f32x4*)(sK + sn * 64), r_n = *(const LAS f32x4*)(sR + sn * 64);
;                             const float v = vq[u16 >> 2][u16 & 3];
;                             const f32x2 vv = {v, v};
;                             f32x2 pp = S01 * (f32x2){a_[0], a_[1]}; pp = S23 * (f32x2){a_[2], a_[3]} + pp;
;                             f32x2 yy = S01 * (f32x2){rp[0], rp[1]}; yy = S23 * (f32x2){rp[2], rp[3]} + yy;
;                             float sa = pp[0] + pp[1], y = yy[0] + yy[1];
;                             sa += dpp_f<0xB1>(sa); y += dpp_f<0xB1>(y);
;                             sa += dpp_f<0x4E>(sa); y += dpp_f<0x4E>(y);
;                             sa += dpp_f<0x141>(sa); y += dpp_f<0x141>(y);
;                             sa += dpp_f<0x140>(sa); y += dpp_f<0x140>(y);
;                             sY[((s - 1) & 31) * 16 + srow] = y;
;                             const f32x2 sv = {sa, sa};
;                             S01 = S01 * (f32x2){w_[0], w_[1]} + vv * (f32x2){k_[0], k_[1]};
;                             S23 = S23 * (f32x2){w_[2], w_[3]} + vv * (f32x2){k_[2], k_[3]};
;                             S01 = sv * (f32x2){b_[0], b_[1]} + S01;
;                             S23 = sv * (f32x2){b_[2], b_[3]} + S23;
;                             rp = r_;
;                             a_ = a_n; w_ = w_n; b_ = b_n; k_ = k_n; r_ = r_n;
;                         }
	v_pk_mul_f32 v[114:115], v[166:167], v[22:23]
	v_pk_mul_f32 v[116:117], v[166:167], v[18:19]
	v_pk_fma_f32 v[114:115], v[164:165], v[24:25], v[114:115]
	v_pk_fma_f32 v[116:117], v[164:165], v[20:21], v[116:117]
	v_add_f32_e32 v122, v114, v115
	v_pk_mul_f32 v[118:119], v[106:107], v[34:35] op_sel:[1,0]
	v_add_f32_e32 v210, v116, v117
	v_add_f32_dpp v122, v122, v122 quad_perm:[1,0,3,2] row_mask:0xf bank_mask:0xf bound_ctrl:1
	v_pk_mul_f32 v[120:121], v[106:107], v[36:37] op_sel:[1,0]
	ds_read_b128 v[14:17], v124 offset:23552
	v_add_f32_dpp v122, v122, v122 quad_perm:[2,3,0,1] row_mask:0xf bank_mask:0xf bound_ctrl:1
	v_pk_fma_f32 v[166:167], v[166:167], v[26:27], v[118:119]
	ds_read_b128 v[6:9], v124 offset:15360
	v_add_f32_dpp v122, v122, v122 row_half_mirror row_mask:0xf bank_mask:0xf bound_ctrl:1
	v_pk_fma_f32 v[164:165], v[164:165], v[28:29], v[120:121]
	ds_read_b128 v[10:13], v124 offset:39936
	v_add_f32_dpp v122, v122, v122 row_mirror row_mask:0xf bank_mask:0xf bound_ctrl:1
	v_add_f32_dpp v222, v222, v222 row_half_mirror row_mask:0xf bank_mask:0xf bound_ctrl:1
	v_add_f32_dpp v223, v223, v223 row_half_mirror row_mask:0xf bank_mask:0xf bound_ctrl:1
	v_pk_fma_f32 v[166:167], v[30:31], v[122:123], v[166:167] op_sel_hi:[1,0,1]
	v_pk_fma_f32 v[164:165], v[32:33], v[122:123], v[164:165] op_sel_hi:[1,0,1]
	ds_read_b128 v[18:21], v124 offset:7168
	ds_read_b128 v[2:5], v124 offset:31744
	ds_read_b128 v[110:113], v125 offset:41072
	s_waitcnt lgkmcnt(11)
	v_pk_mul_f32 v[114:115], v[166:167], v[42:43]
	v_pk_mul_f32 v[116:117], v[166:167], v[38:39]
	v_pk_fma_f32 v[114:115], v[164:165], v[44:45], v[114:115]
	v_pk_fma_f32 v[116:117], v[164:165], v[40:41], v[116:117]
	v_add_f32_e32 v122, v114, v115
	v_pk_mul_f32 v[118:119], v[108:109], v[54:55] op_sel_hi:[0,1]
	v_add_f32_e32 v211, v116, v117
	v_add_f32_dpp v122, v122, v122 quad_perm:[1,0,3,2] row_mask:0xf bank_mask:0xf bound_ctrl:1
	v_pk_mul_f32 v[120:121], v[108:109], v[56:57] op_sel_hi:[0,1]
	ds_read_b128 v[34:37], v124 offset:23808
	v_add_f32_dpp v122, v122, v122 quad_perm:[2,3,0,1] row_mask:0xf bank_mask:0xf bound_ctrl:1
	v_pk_fma_f32 v[166:167], v[166:167], v[46:47], v[118:119]
	ds_read_b128 v[26:29], v124 offset:15616
	v_add_f32_dpp v122, v122, v122 row_half_mirror row_mask:0xf bank_mask:0xf bound_ctrl:1
	v_pk_fma_f32 v[164:165], v[164:165], v[48:49], v[120:121]
	ds_read_b128 v[30:33], v124 offset:40192
	v_add_f32_dpp v122, v122, v122 row_mirror row_mask:0xf bank_mask:0xf bound_ctrl:1
	v_add_f32_dpp v220, v224, v224 row_half_mirror row_mask:0xf bank_mask:0xa bound_ctrl:1
	v_add_f32_dpp v221, v225, v225 row_half_mirror row_mask:0xf bank_mask:0xa bound_ctrl:1
	v_pk_fma_f32 v[166:167], v[50:51], v[122:123], v[166:167] op_sel_hi:[1,0,1]
	v_pk_fma_f32 v[164:165], v[52:53], v[122:123], v[164:165] op_sel_hi:[1,0,1]
	ds_read_b128 v[38:41], v124 offset:7424
	ds_read_b128 v[22:25], v124 offset:32000
	s_waitcnt lgkmcnt(11)
	v_pk_mul_f32 v[114:115], v[166:167], v[62:63]
	v_pk_mul_f32 v[116:117], v[166:167], v[58:59]
	v_pk_fma_f32 v[114:115], v[164:165], v[64:65], v[114:115]
	v_pk_fma_f32 v[116:117], v[164:165], v[60:61], v[116:117]
	v_add_f32_e32 v122, v114, v115
	v_pk_mul_f32 v[118:119], v[108:109], v[74:75] op_sel:[1,0]
	v_add_f32_e32 v212, v116, v117
	v_add_f32_dpp v122, v122, v122 quad_perm:[1,0,3,2] row_mask:0xf bank_mask:0xf bound_ctrl:1
	v_pk_mul_f32 v[120:121], v[108:109], v[76:77] op_sel:[1,0]
	ds_read_b128 v[54:57], v124 offset:24064
	v_add_f32_dpp v122, v122, v122 quad_perm:[2,3,0,1] row_mask:0xf bank_mask:0xf bound_ctrl:1
	v_pk_fma_f32 v[166:167], v[166:167], v[66:67], v[118:119]
	ds_read_b128 v[46:49], v124 offset:15872
	v_add_f32_dpp v122, v122, v122 row_half_mirror row_mask:0xf bank_mask:0xf bound_ctrl:1
	v_pk_fma_f32 v[164:165], v[164:165], v[68:69], v[120:121]
	ds_read_b128 v[50:53], v124 offset:40448
	v_add_f32_dpp v122, v122, v122 row_mirror row_mask:0xf bank_mask:0xf bound_ctrl:1
	v_add_f32_dpp v222, v226, v226 row_half_mirror row_mask:0xf bank_mask:0xa bound_ctrl:1
	v_add_f32_dpp v223, v227, v227 row_half_mirror row_mask:0xf bank_mask:0xa bound_ctrl:1
	v_pk_fma_f32 v[166:167], v[70:71], v[122:123], v[166:167] op_sel_hi:[1,0,1]
	v_pk_fma_f32 v[164:165], v[72:73], v[122:123], v[164:165] op_sel_hi:[1,0,1]
	ds_read_b128 v[58:61], v124 offset:7680
	ds_read_b128 v[42:45], v124 offset:32256
	s_waitcnt lgkmcnt(11)
	v_pk_mul_f32 v[114:115], v[166:167], v[2:3]
	v_pk_mul_f32 v[116:117], v[166:167], v[78:79]
	v_pk_fma_f32 v[114:115], v[164:165], v[4:5], v[114:115]
	v_pk_fma_f32 v[116:117], v[164:165], v[80:81], v[116:117]
	v_add_f32_e32 v122, v114, v115
	s_waitcnt lgkmcnt(10)
	v_pk_mul_f32 v[118:119], v[110:111], v[14:15] op_sel_hi:[0,1]
	v_add_f32_e32 v213, v116, v117
	v_add_f32_dpp v122, v122, v122 quad_perm:[1,0,3,2] row_mask:0xf bank_mask:0xf bound_ctrl:1
	v_pk_mul_f32 v[120:121], v[110:111], v[16:17] op_sel_hi:[0,1]
	ds_read_b128 v[74:77], v124 offset:24320
	v_add_f32_dpp v122, v122, v122 quad_perm:[2,3,0,1] row_mask:0xf bank_mask:0xf bound_ctrl:1
	v_pk_fma_f32 v[166:167], v[166:167], v[6:7], v[118:119]
	ds_read_b128 v[66:69], v124 offset:16128
	v_add_f32_dpp v122, v122, v122 row_half_mirror row_mask:0xf bank_mask:0xf bound_ctrl:1
	v_pk_fma_f32 v[164:165], v[164:165], v[8:9], v[120:121]
	ds_read_b128 v[70:73], v124 offset:40704
	v_add_f32_dpp v122, v122, v122 row_mirror row_mask:0xf bank_mask:0xf bound_ctrl:1
	v_add_f32_dpp v220, v220, v220 quad_perm:[1,0,3,2] row_mask:0xf bank_mask:0xf bound_ctrl:1
	v_add_f32_dpp v221, v221, v221 quad_perm:[1,0,3,2] row_mask:0xf bank_mask:0xf bound_ctrl:1
	v_pk_fma_f32 v[166:167], v[10:11], v[122:123], v[166:167] op_sel_hi:[1,0,1]
	v_pk_fma_f32 v[164:165], v[12:13], v[122:123], v[164:165] op_sel_hi:[1,0,1]
	ds_read_b128 v[78:81], v124 offset:7936
	ds_read_b128 v[62:65], v124 offset:32512
	v_add_f32_dpp v222, v222, v222 quad_perm:[1,0,3,2] row_mask:0xf bank_mask:0xf bound_ctrl:1
	v_add_f32_dpp v223, v223, v223 quad_perm:[1,0,3,2] row_mask:0xf bank_mask:0xf bound_ctrl:1
	v_add_f32_dpp v220, v220, v220 quad_perm:[2,3,0,1] row_mask:0xf bank_mask:0xf bound_ctrl:1
	v_add_f32_dpp v221, v221, v221 quad_perm:[2,3,0,1] row_mask:0xf bank_mask:0xf bound_ctrl:1
	v_add_f32_dpp v222, v222, v222 quad_perm:[2,3,0,1] row_mask:0xf bank_mask:0xf bound_ctrl:1
	v_add_f32_dpp v223, v223, v223 quad_perm:[2,3,0,1] row_mask:0xf bank_mask:0xf bound_ctrl:1
	v_cndmask_b32_e64 v202, v220, v221, s[34:35]
	v_cndmask_b32_e64 v202, v202, v222, s[56:57]
	v_cndmask_b32_e64 v202, v202, v223, s[98:99]
	v_cvt_f16_f32_e32 v203, v202
	global_store_short v[126:127], v203, off
	v_lshl_add_u64 v[126:127], v[126:127], 0, s[100:101]
	s_setprio 0
	s_branch .LBB0_603
; template <int CTRL> __device__ __forceinline__ float dpp_f(float x) { return __int_as_float(__builtin_amdgcn_update_dpp(0, __float_as_int(x), CTRL, 0xf, 0xf, false)); }
; __device__ __forceinline__ void phase_scan(const Params& p, LAS unsigned char* lds) {
;     ...
;                             const float v = vq[u16 >> 2][u16 & 3];
;                             const f32x2 vv = {v, v};
;                             f32x2 pp = S01 * (f32x2){a_[0], a_[1]}; pp = S23 * (f32x2){a_[2], a_[3]} + pp;
;                             f32x2 yy = S01 * (f32x2){rp[0], rp[1]}; yy = S23 * (f32x2){rp[2], rp[3]} + yy;
;                             float sa = pp[0] + pp[1], y = yy[0] + yy[1];
;                             sa += dpp_f<0xB1>(sa); y += dpp_f<0xB1>(y);
;                             sa += dpp_f<0x4E>(sa); y += dpp_f<0x4E>(y);
;                             sa += dpp_f<0x141>(sa); y += dpp_f<0x141>(y);
;                             sa += dpp_f<0x140>(sa); y += dpp_f<0x140>(y);
;                             sY[((s - 1) & 31) * 16 + srow] = y;
;                             const f32x2 sv = {sa, sa};
;                             S01 = S01 * (f32x2){w_[0], w_[1]} + vv * (f32x2){k_[0], k_[1]};
;                             S23 = S23 * (f32x2){w_[2], w_[3]} + vv * (f32x2){k_[2], k_[3]};
;                             S01 = sv * (f32x2){b_[0], b_[1]} + S01;
;                             S23 = sv * (f32x2){b_[2], b_[3]} + S23;
;                             rp = r_;
;                             a_ = a_n; w_ = w_n; b_ = b_n; k_ = k_n; r_ = r_n;
;                         }
; #pragma unroll
;                         for (int u = 0; u < 4; ++u) vq[u] = vn[u];
;                     }
;                     { f32x2 yy = S01 * (f32x2){rp[0], rp[1]}; yy = S23 * (f32x2){rp[2], rp[3]} + yy; sY[31 * 16 + srow] = red16(yy[0] + yy[1]); }
;     ...
;         if (wave >= 4) SCAN_YSTORE(SEQ / 32 - 1);
.LBB0_620:
	s_mov_b64 s[10:11], 0
	s_cmp_eq_u64 s[0:1], 0
	s_cbranch_scc0 .LBB0_594
	s_setprio 3
	s_mov_b32 s14, 0x3fff3fff
	s_mov_b32 s15, s14
	v_pk_mul_f32 v[114:115], v[166:167], v[22:23]
	v_pk_mul_f32 v[116:117], v[166:167], v[18:19]
	v_pk_fma_f32 v[114:115], v[164:165], v[24:25], v[114:115]
	v_pk_fma_f32 v[116:117], v[164:165], v[20:21], v[116:117]
	v_add_f32_e32 v122, v114, v115
	v_pk_mul_f32 v[118:119], v[110:111], v[34:35] op_sel:[1,0]
	v_add_f32_e32 v214, v116, v117
	v_add_f32_dpp v122, v122, v122 quad_perm:[1,0,3,2] row_mask:0xf bank_mask:0xf bound_ctrl:1
	v_pk_mul_f32 v[120:121], v[110:111], v[36:37] op_sel:[1,0]
	v_add_f32_dpp v204, v204, v204 row_mirror row_mask:0xf bank_mask:0xf bound_ctrl:1
	v_add_f32_dpp v122, v122, v122 quad_perm:[2,3,0,1] row_mask:0xf bank_mask:0xf bound_ctrl:1
	v_pk_fma_f32 v[166:167], v[166:167], v[26:27], v[118:119]
	v_add_f32_dpp v204, v212, v212 row_mirror row_mask:0xf bank_mask:0xc bound_ctrl:1
	v_add_f32_dpp v122, v122, v122 row_half_mirror row_mask:0xf bank_mask:0xf bound_ctrl:1
	v_pk_fma_f32 v[164:165], v[164:165], v[28:29], v[120:121]
	v_add_f32_dpp v205, v205, v205 row_mirror row_mask:0xf bank_mask:0xf bound_ctrl:1
	v_add_f32_dpp v122, v122, v122 row_mirror row_mask:0xf bank_mask:0xf bound_ctrl:1
	v_add_f32_dpp v205, v213, v213 row_mirror row_mask:0xf bank_mask:0xc bound_ctrl:1
	v_add_f32_dpp v206, v206, v206 row_mirror row_mask:0xf bank_mask:0xf bound_ctrl:1
	v_pk_fma_f32 v[166:167], v[30:31], v[122:123], v[166:167] op_sel_hi:[1,0,1]
	v_pk_fma_f32 v[164:165], v[32:33], v[122:123], v[164:165] op_sel_hi:[1,0,1]
	v_pk_mul_f32 v[114:115], v[166:167], v[42:43]
	v_pk_mul_f32 v[116:117], v[166:167], v[38:39]
	v_pk_fma_f32 v[114:115], v[164:165], v[44:45], v[114:115]
	v_pk_fma_f32 v[116:117], v[164:165], v[40:41], v[116:117]
	v_add_f32_e32 v122, v114, v115
	v_pk_mul_f32 v[118:119], v[112:113], v[54:55] op_sel_hi:[0,1]
	v_add_f32_e32 v215, v116, v117
	v_add_f32_dpp v122, v122, v122 quad_perm:[1,0,3,2] row_mask:0xf bank_mask:0xf bound_ctrl:1
	v_pk_mul_f32 v[120:121], v[112:113], v[56:57] op_sel_hi:[0,1]
	v_add_f32_dpp v206, v214, v214 row_mirror row_mask:0xf bank_mask:0xc bound_ctrl:1
	v_add_f32_dpp v122, v122, v122 quad_perm:[2,3,0,1] row_mask:0xf bank_mask:0xf bound_ctrl:1
	v_pk_fma_f32 v[166:167], v[166:167], v[46:47], v[118:119]
	v_add_f32_dpp v207, v207, v207 row_mirror row_mask:0xf bank_mask:0xf bound_ctrl:1
	v_add_f32_dpp v122, v122, v122 row_half_mirror row_mask:0xf bank_mask:0xf bound_ctrl:1
	v_pk_fma_f32 v[164:165], v[164:165], v[48:49], v[120:121]
	v_add_f32_dpp v207, v215, v215 row_mirror row_mask:0xf bank_mask:0xc bound_ctrl:1
	v_add_f32_dpp v122, v122, v122 row_mirror row_mask:0xf bank_mask:0xf bound_ctrl:1
	s_nop 0
	v_pk_fma_f32 v[166:167], v[50:51], v[122:123], v[166:167] op_sel_hi:[1,0,1]
	v_pk_fma_f32 v[164:165], v[52:53], v[122:123], v[164:165] op_sel_hi:[1,0,1]
	v_pk_mul_f32 v[114:115], v[166:167], v[62:63]
	v_pk_mul_f32 v[116:117], v[166:167], v[58:59]
	v_pk_fma_f32 v[114:115], v[164:165], v[64:65], v[114:115]
	v_pk_fma_f32 v[116:117], v[164:165], v[60:61], v[116:117]
	v_add_f32_e32 v122, v114, v115
	v_pk_mul_f32 v[118:119], v[112:113], v[74:75] op_sel:[1,0]
	v_add_f32_e32 v216, v116, v117
	v_add_f32_dpp v122, v122, v122 quad_perm:[1,0,3,2] row_mask:0xf bank_mask:0xf bound_ctrl:1
	v_pk_mul_f32 v[120:121], v[112:113], v[76:77] op_sel:[1,0]
	v_add_f32_dpp v208, v208, v208 row_mirror row_mask:0xf bank_mask:0xf bound_ctrl:1
	v_add_f32_dpp v122, v122, v122 quad_perm:[2,3,0,1] row_mask:0xf bank_mask:0xf bound_ctrl:1
	v_pk_fma_f32 v[166:167], v[166:167], v[66:67], v[118:119]
	v_add_f32_dpp v208, v216, v216 row_mirror row_mask:0xf bank_mask:0xc bound_ctrl:1
	v_add_f32_dpp v122, v122, v122 row_half_mirror row_mask:0xf bank_mask:0xf bound_ctrl:1
	v_pk_fma_f32 v[164:165], v[164:165], v[68:69], v[120:121]
	s_nop 0
	v_add_f32_dpp v122, v122, v122 row_mirror row_mask:0xf bank_mask:0xf bound_ctrl:1
	s_nop 0
	v_pk_fma_f32 v[166:167], v[70:71], v[122:123], v[166:167] op_sel_hi:[1,0,1]
	v_pk_fma_f32 v[164:165], v[72:73], v[122:123], v[164:165] op_sel_hi:[1,0,1]
	v_pk_mul_f32 v[116:117], v[166:167], v[78:79]
	s_nop 0
	v_pk_fma_f32 v[116:117], v[164:165], v[80:81], v[116:117]
	s_nop 0
	v_add_f32_e32 v217, v116, v117
	v_mov_b32_e32 v218, 0
	v_mov_b32_e32 v219, 0
	s_nop 1
	v_add_f32_dpp v209, v209, v209 row_mirror row_mask:0xf bank_mask:0xf bound_ctrl:1
	v_add_f32_dpp v209, v217, v217 row_mirror row_mask:0xf bank_mask:0xc bound_ctrl:1
	v_add_f32_dpp v210, v210, v210 row_mirror row_mask:0xf bank_mask:0xf bound_ctrl:1
	v_add_f32_dpp v210, v218, v218 row_mirror row_mask:0xf bank_mask:0xc bound_ctrl:1
	v_add_f32_dpp v211, v211, v211 row_mirror row_mask:0xf bank_mask:0xf bound_ctrl:1
	v_add_f32_dpp v211, v219, v219 row_mirror row_mask:0xf bank_mask:0xc bound_ctrl:1
	s_nop 1
	v_add_f32_dpp v204, v204, v204 row_half_mirror row_mask:0xf bank_mask:0xf bound_ctrl:1
	v_add_f32_dpp v205, v205, v205 row_half_mirror row_mask:0xf bank_mask:0xf bound_ctrl:1
	v_add_f32_dpp v206, v206, v206 row_half_mirror row_mask:0xf bank_mask:0xf bound_ctrl:1
	v_add_f32_dpp v207, v207, v207 row_half_mirror row_mask:0xf bank_mask:0xf bound_ctrl:1
	v_add_f32_dpp v204, v208, v208 row_half_mirror row_mask:0xf bank_mask:0xa bound_ctrl:1
	v_add_f32_dpp v205, v209, v209 row_half_mirror row_mask:0xf bank_mask:0xa bound_ctrl:1
	v_add_f32_dpp v206, v210, v210 row_half_mirror row_mask:0xf bank_mask:0xa bound_ctrl:1
	v_add_f32_dpp v207, v211, v211 row_half_mirror row_mask:0xf bank_mask:0xa bound_ctrl:1
	v_add_f32_dpp v204, v204, v204 quad_perm:[1,0,3,2] row_mask:0xf bank_mask:0xf bound_ctrl:1
	v_add_f32_dpp v205, v205, v205 quad_perm:[1,0,3,2] row_mask:0xf bank_mask:0xf bound_ctrl:1
	v_add_f32_dpp v206, v206, v206 quad_perm:[1,0,3,2] row_mask:0xf bank_mask:0xf bound_ctrl:1
	v_add_f32_dpp v207, v207, v207 quad_perm:[1,0,3,2] row_mask:0xf bank_mask:0xf bound_ctrl:1
	v_add_f32_dpp v204, v204, v204 quad_perm:[2,3,0,1] row_mask:0xf bank_mask:0xf bound_ctrl:1
	v_add_f32_dpp v205, v205, v205 quad_perm:[2,3,0,1] row_mask:0xf bank_mask:0xf bound_ctrl:1
	v_add_f32_dpp v206, v206, v206 quad_perm:[2,3,0,1] row_mask:0xf bank_mask:0xf bound_ctrl:1
	v_add_f32_dpp v207, v207, v207 quad_perm:[2,3,0,1] row_mask:0xf bank_mask:0xf bound_ctrl:1
	v_cndmask_b32_e64 v202, v204, v205, s[34:35]
	v_cndmask_b32_e64 v202, v202, v206, s[56:57]
	v_cndmask_b32_e64 v202, v202, v207, s[98:99]
	v_cvt_f16_f32_e32 v203, v202
	s_mov_b64 exec, s[14:15]
	global_store_short v[128:129], v203, off
	s_mov_b64 exec, -1
	v_lshl_add_u64 v[128:129], v[128:129], 0, s[100:101]
	s_setprio 0
	s_branch .LBB0_594
